# v41 plus deletion of all per-block s_setprio flips in the GEMM K loops (A/B of the compiler's priority toggles)
# baseline (speedup 1.0000x reference)
.LBB0_307:
	s_add_u32 vcc_lo, s82, 0x80
	s_addc_u32 vcc_hi, s83, 0
	s_add_u32 s82, s42, 0x100
	s_addc_u32 s83, s43, 0
	s_mov_b32 s42, 0
	s_add_i32 s72, s42, 2
	s_add_u32 s73, vcc_lo, 0x80
	s_addc_u32 s43, vcc_hi, 0
	s_add_i32 s45, 0, 0x10000
	s_cmp_eq_u32 s63, s42
	s_cselect_b32 s43, s9, s43
	s_cselect_b32 s42, s8, s73
	v_add_u32_e32 v140, s45, v143
	s_cselect_b32 s75, s91, s83
	s_cselect_b32 s74, s90, s82
	s_add_i32 s73, 0, 0x14000
	ds_read_b128 v[146:149], v140
	ds_read_b128 v[150:153], v140 offset:1024
	ds_read_b128 v[154:157], v140 offset:2048
	ds_read_b128 v[158:161], v140 offset:3072
	v_add_u32_e32 v140, s73, v143
	ds_read_b128 v[162:165], v140
	ds_read_b128 v[166:169], v140 offset:1024
	ds_read_b128 v[170:173], v140 offset:2048
	ds_read_b128 v[174:177], v140 offset:3072
	v_lshl_add_u64 v[140:141], vcc, 0, v[136:137]
	s_add_i32 m0, s59, 0xc000
	ds_read_b128 v[178:181], v145
	ds_read_b128 v[182:185], v145 offset:1024
	ds_read_b128 v[186:189], v145 offset:2048
	ds_read_b128 v[190:193], v145 offset:3072
	ds_read_b128 v[202:205], v145 offset:4096
	ds_read_b128 v[206:209], v145 offset:5120
	ds_read_b128 v[220:223], v145 offset:6144
	ds_read_b128 v[224:227], v145 offset:7168
	global_load_lds_dwordx4 v[140:141], off
	v_lshl_add_u64 v[140:141], vcc, 0, v[138:139]
	s_add_i32 m0, s59, 0xe000
	s_nop 0
	global_load_lds_dwordx4 v[140:141], off
	s_waitcnt vmcnt(8)
	s_waitcnt lgkmcnt(0)
	s_barrier
	s_waitcnt lgkmcnt(0)
	v_mfma_f32_16x16x32_bf16 v[126:129], v[146:149], v[178:181], 0
	v_mfma_f32_16x16x32_bf16 v[122:125], v[154:157], v[178:181], 0
	v_mfma_f32_16x16x32_bf16 v[118:121], v[146:149], v[186:189], 0
	v_mfma_f32_16x16x32_bf16 v[110:113], v[154:157], v[186:189], 0
	v_mfma_f32_16x16x32_bf16 v[102:105], v[146:149], v[202:205], 0
	v_mfma_f32_16x16x32_bf16 v[94:97], v[154:157], v[202:205], 0
	v_mfma_f32_16x16x32_bf16 v[86:89], v[146:149], v[220:223], 0
	v_mfma_f32_16x16x32_bf16 v[78:81], v[154:157], v[220:223], 0
	v_mfma_f32_16x16x32_bf16 v[126:129], v[150:153], v[182:185], v[126:129]
	v_mfma_f32_16x16x32_bf16 v[122:125], v[158:161], v[182:185], v[122:125]
	v_mfma_f32_16x16x32_bf16 v[118:121], v[150:153], v[190:193], v[118:121]
	v_mfma_f32_16x16x32_bf16 v[110:113], v[158:161], v[190:193], v[110:113]
	v_mfma_f32_16x16x32_bf16 v[102:105], v[150:153], v[206:209], v[102:105]
	v_mfma_f32_16x16x32_bf16 v[94:97], v[158:161], v[206:209], v[94:97]
	v_mfma_f32_16x16x32_bf16 v[86:89], v[150:153], v[224:227], v[86:89]
	v_mfma_f32_16x16x32_bf16 v[78:81], v[158:161], v[224:227], v[78:81]
	v_mfma_f32_16x16x32_bf16 v[114:117], v[162:165], v[178:181], 0
	v_mfma_f32_16x16x32_bf16 v[106:109], v[170:173], v[178:181], 0
	v_mfma_f32_16x16x32_bf16 v[98:101], v[162:165], v[186:189], 0
	v_mfma_f32_16x16x32_bf16 v[90:93], v[170:173], v[186:189], 0
	v_mfma_f32_16x16x32_bf16 v[82:85], v[162:165], v[202:205], 0
	v_mfma_f32_16x16x32_bf16 v[74:77], v[170:173], v[202:205], 0
	v_mfma_f32_16x16x32_bf16 v[70:73], v[162:165], v[220:223], 0
	v_mfma_f32_16x16x32_bf16 v[66:69], v[170:173], v[220:223], 0
	v_mfma_f32_16x16x32_bf16 v[114:117], v[166:169], v[182:185], v[114:117]
	v_mfma_f32_16x16x32_bf16 v[106:109], v[174:177], v[182:185], v[106:109]
	v_mfma_f32_16x16x32_bf16 v[98:101], v[166:169], v[190:193], v[98:101]
	v_mfma_f32_16x16x32_bf16 v[90:93], v[174:177], v[190:193], v[90:93]
	v_mfma_f32_16x16x32_bf16 v[82:85], v[166:169], v[206:209], v[82:85]
	v_mfma_f32_16x16x32_bf16 v[74:77], v[174:177], v[206:209], v[74:77]
	v_mfma_f32_16x16x32_bf16 v[70:73], v[166:169], v[224:227], v[70:73]
	v_mfma_f32_16x16x32_bf16 v[66:69], v[174:177], v[224:227], v[66:69]
	s_barrier
	s_add_i32 s45, s45, s54
	v_lshl_add_u64 v[140:141], s[74:75], 0, v[0:1]
	s_mov_b32 m0, s45
	ds_read_b128 v[178:181], v145 offset:16384
	ds_read_b128 v[182:185], v145 offset:17408
	ds_read_b128 v[186:189], v145 offset:18432
	ds_read_b128 v[190:193], v145 offset:19456
	ds_read_b128 v[202:205], v145 offset:20480
	ds_read_b128 v[206:209], v145 offset:21504
	ds_read_b128 v[220:223], v145 offset:22528
	ds_read_b128 v[224:227], v145 offset:23552
	global_load_lds_dwordx4 v[140:141], off
	s_add_i32 m0, s45, 0x2000
	v_lshl_add_u64 v[194:195], s[74:75], 0, v[134:135]
	s_add_u32 s74, s74, s80
	s_addc_u32 s75, s75, 0
	s_add_i32 s45, s73, s54
	global_load_lds_dwordx4 v[194:195], off
	v_lshl_add_u64 v[198:199], s[74:75], 0, v[0:1]
	s_mov_b32 m0, s45
	v_lshl_add_u64 v[200:201], s[74:75], 0, v[134:135]
	global_load_lds_dwordx4 v[198:199], off
	s_add_i32 m0, s45, 0x2000
	v_lshl_add_u64 v[210:211], s[42:43], 0, v[130:131]
	global_load_lds_dwordx4 v[200:201], off
	s_mov_b32 m0, s59
	v_lshl_add_u64 v[212:213], s[42:43], 0, v[132:133]
	global_load_lds_dwordx4 v[210:211], off
	s_mov_b32 m0, s60
	s_nop 0
	global_load_lds_dwordx4 v[212:213], off
	s_waitcnt vmcnt(8)
	s_waitcnt lgkmcnt(0)
	s_barrier
	s_waitcnt lgkmcnt(0)
	v_mfma_f32_16x16x32_bf16 v[62:65], v[146:149], v[178:181], 0
	v_mfma_f32_16x16x32_bf16 v[58:61], v[154:157], v[178:181], 0
	v_mfma_f32_16x16x32_bf16 v[54:57], v[146:149], v[186:189], 0
	v_mfma_f32_16x16x32_bf16 v[46:49], v[154:157], v[186:189], 0
	v_mfma_f32_16x16x32_bf16 v[38:41], v[146:149], v[202:205], 0
	v_mfma_f32_16x16x32_bf16 v[30:33], v[154:157], v[202:205], 0
	v_mfma_f32_16x16x32_bf16 v[22:25], v[146:149], v[220:223], 0
	v_mfma_f32_16x16x32_bf16 v[14:17], v[154:157], v[220:223], 0
	v_mfma_f32_16x16x32_bf16 v[62:65], v[150:153], v[182:185], v[62:65]
	v_mfma_f32_16x16x32_bf16 v[58:61], v[158:161], v[182:185], v[58:61]
	v_mfma_f32_16x16x32_bf16 v[54:57], v[150:153], v[190:193], v[54:57]
	v_mfma_f32_16x16x32_bf16 v[46:49], v[158:161], v[190:193], v[46:49]
	v_mfma_f32_16x16x32_bf16 v[38:41], v[150:153], v[206:209], v[38:41]
	v_mfma_f32_16x16x32_bf16 v[30:33], v[158:161], v[206:209], v[30:33]
	v_mfma_f32_16x16x32_bf16 v[22:25], v[150:153], v[224:227], v[22:25]
	v_mfma_f32_16x16x32_bf16 v[14:17], v[158:161], v[224:227], v[14:17]
	v_mfma_f32_16x16x32_bf16 v[50:53], v[162:165], v[178:181], 0
	v_mfma_f32_16x16x32_bf16 v[42:45], v[170:173], v[178:181], 0
	v_mfma_f32_16x16x32_bf16 v[34:37], v[162:165], v[186:189], 0
	v_mfma_f32_16x16x32_bf16 v[26:29], v[170:173], v[186:189], 0
	v_mfma_f32_16x16x32_bf16 v[18:21], v[162:165], v[202:205], 0
	v_mfma_f32_16x16x32_bf16 v[10:13], v[170:173], v[202:205], 0
	v_mfma_f32_16x16x32_bf16 v[6:9], v[162:165], v[220:223], 0
	v_mfma_f32_16x16x32_bf16 v[2:5], v[170:173], v[220:223], 0
	v_mfma_f32_16x16x32_bf16 v[50:53], v[166:169], v[182:185], v[50:53]
	v_mfma_f32_16x16x32_bf16 v[42:45], v[174:177], v[182:185], v[42:45]
	v_mfma_f32_16x16x32_bf16 v[34:37], v[166:169], v[190:193], v[34:37]
	v_mfma_f32_16x16x32_bf16 v[26:29], v[174:177], v[190:193], v[26:29]
	v_mfma_f32_16x16x32_bf16 v[18:21], v[166:169], v[206:209], v[18:21]
	v_mfma_f32_16x16x32_bf16 v[10:13], v[174:177], v[206:209], v[10:13]
	v_mfma_f32_16x16x32_bf16 v[6:9], v[166:169], v[224:227], v[6:9]
	v_mfma_f32_16x16x32_bf16 v[2:5], v[174:177], v[224:227], v[2:5]
	s_barrier
	s_add_i32 s45, 0, 0x18000
	s_add_i32 s73, 0, 0x1c000
	v_add_u32_e32 v158, s45, v143
	v_add_u32_e32 v174, s73, v143
	ds_read_b128 v[146:149], v158
	ds_read_b128 v[150:153], v158 offset:1024
	ds_read_b128 v[154:157], v158 offset:2048
	ds_read_b128 v[158:161], v158 offset:3072
	ds_read_b128 v[162:165], v174
	ds_read_b128 v[166:169], v174 offset:1024
	ds_read_b128 v[170:173], v174 offset:2048
	ds_read_b128 v[174:177], v174 offset:3072
	s_add_u32 s42, s42, s80
	s_addc_u32 s43, s43, 0
	s_mov_b32 m0, s61
	v_lshl_add_u64 v[214:215], s[42:43], 0, v[130:131]
	ds_read_b128 v[178:181], v145 offset:32768
	ds_read_b128 v[182:185], v145 offset:33792
	ds_read_b128 v[186:189], v145 offset:34816
	ds_read_b128 v[190:193], v145 offset:35840
	ds_read_b128 v[202:205], v145 offset:36864
	ds_read_b128 v[206:209], v145 offset:37888
	ds_read_b128 v[220:223], v145 offset:38912
	ds_read_b128 v[224:227], v145 offset:39936
	global_load_lds_dwordx4 v[214:215], off
	v_lshl_add_u64 v[214:215], s[42:43], 0, v[132:133]
	s_mov_b32 m0, s62
	s_nop 0
	global_load_lds_dwordx4 v[214:215], off
	s_waitcnt vmcnt(8)
	s_waitcnt lgkmcnt(0)
	s_barrier
	s_waitcnt lgkmcnt(0)
	v_mfma_f32_16x16x32_bf16 v[126:129], v[146:149], v[178:181], v[126:129]
	v_mfma_f32_16x16x32_bf16 v[122:125], v[154:157], v[178:181], v[122:125]
	v_mfma_f32_16x16x32_bf16 v[118:121], v[146:149], v[186:189], v[118:121]
	v_mfma_f32_16x16x32_bf16 v[110:113], v[154:157], v[186:189], v[110:113]
	v_mfma_f32_16x16x32_bf16 v[102:105], v[146:149], v[202:205], v[102:105]
	v_mfma_f32_16x16x32_bf16 v[94:97], v[154:157], v[202:205], v[94:97]
	v_mfma_f32_16x16x32_bf16 v[86:89], v[146:149], v[220:223], v[86:89]
	v_mfma_f32_16x16x32_bf16 v[78:81], v[154:157], v[220:223], v[78:81]
	v_mfma_f32_16x16x32_bf16 v[126:129], v[150:153], v[182:185], v[126:129]
	v_mfma_f32_16x16x32_bf16 v[122:125], v[158:161], v[182:185], v[122:125]
	v_mfma_f32_16x16x32_bf16 v[118:121], v[150:153], v[190:193], v[118:121]
	v_mfma_f32_16x16x32_bf16 v[110:113], v[158:161], v[190:193], v[110:113]
	v_mfma_f32_16x16x32_bf16 v[102:105], v[150:153], v[206:209], v[102:105]
	v_mfma_f32_16x16x32_bf16 v[94:97], v[158:161], v[206:209], v[94:97]
	v_mfma_f32_16x16x32_bf16 v[86:89], v[150:153], v[224:227], v[86:89]
	v_mfma_f32_16x16x32_bf16 v[78:81], v[158:161], v[224:227], v[78:81]
	v_mfma_f32_16x16x32_bf16 v[114:117], v[162:165], v[178:181], v[114:117]
	v_mfma_f32_16x16x32_bf16 v[106:109], v[170:173], v[178:181], v[106:109]
	v_mfma_f32_16x16x32_bf16 v[98:101], v[162:165], v[186:189], v[98:101]
	v_mfma_f32_16x16x32_bf16 v[90:93], v[170:173], v[186:189], v[90:93]
	v_mfma_f32_16x16x32_bf16 v[82:85], v[162:165], v[202:205], v[82:85]
	v_mfma_f32_16x16x32_bf16 v[74:77], v[170:173], v[202:205], v[74:77]
	v_mfma_f32_16x16x32_bf16 v[70:73], v[162:165], v[220:223], v[70:73]
	v_mfma_f32_16x16x32_bf16 v[66:69], v[170:173], v[220:223], v[66:69]
	v_mfma_f32_16x16x32_bf16 v[114:117], v[166:169], v[182:185], v[114:117]
	v_mfma_f32_16x16x32_bf16 v[106:109], v[174:177], v[182:185], v[106:109]
	v_mfma_f32_16x16x32_bf16 v[98:101], v[166:169], v[190:193], v[98:101]
	v_mfma_f32_16x16x32_bf16 v[90:93], v[174:177], v[190:193], v[90:93]
	v_mfma_f32_16x16x32_bf16 v[82:85], v[166:169], v[206:209], v[82:85]
	v_mfma_f32_16x16x32_bf16 v[74:77], v[174:177], v[206:209], v[74:77]
	v_mfma_f32_16x16x32_bf16 v[70:73], v[166:169], v[224:227], v[70:73]
	v_mfma_f32_16x16x32_bf16 v[66:69], v[174:177], v[224:227], v[66:69]
	s_barrier
	s_add_i32 s42, s45, s54
	v_lshl_add_u64 v[140:141], v[140:141], 0, s[84:85]
	s_mov_b32 m0, s42
	ds_read_b128 v[178:181], v145 offset:49152
	ds_read_b128 v[182:185], v145 offset:50176
	ds_read_b128 v[186:189], v145 offset:51200
	ds_read_b128 v[190:193], v145 offset:52224
	ds_read_b128 v[202:205], v145 offset:53248
	ds_read_b128 v[206:209], v145 offset:54272
	ds_read_b128 v[220:223], v145 offset:55296
	ds_read_b128 v[224:227], v145 offset:56320
	global_load_lds_dwordx4 v[140:141], off
	v_lshl_add_u64 v[140:141], v[194:195], 0, s[84:85]
	s_add_i32 m0, s42, 0x2000
	s_add_i32 s42, s73, s54
	global_load_lds_dwordx4 v[140:141], off
	v_lshl_add_u64 v[140:141], v[198:199], 0, s[84:85]
	s_mov_b32 m0, s42
	s_nop 0
	global_load_lds_dwordx4 v[140:141], off
	v_lshl_add_u64 v[140:141], v[200:201], 0, s[84:85]
	s_add_i32 m0, s42, 0x2000
	s_nop 0
	global_load_lds_dwordx4 v[140:141], off
	v_lshl_add_u64 v[140:141], v[210:211], 0, s[84:85]
	s_mov_b32 m0, s64
	s_nop 0
	global_load_lds_dwordx4 v[140:141], off
	v_lshl_add_u64 v[140:141], v[212:213], 0, s[84:85]
	s_mov_b32 m0, s65
	s_nop 0
	global_load_lds_dwordx4 v[140:141], off
	s_waitcnt vmcnt(8)
	s_waitcnt lgkmcnt(0)
	s_barrier
	s_waitcnt lgkmcnt(0)
	v_mfma_f32_16x16x32_bf16 v[62:65], v[146:149], v[178:181], v[62:65]
	v_mfma_f32_16x16x32_bf16 v[58:61], v[154:157], v[178:181], v[58:61]
	v_mfma_f32_16x16x32_bf16 v[54:57], v[146:149], v[186:189], v[54:57]
	v_mfma_f32_16x16x32_bf16 v[46:49], v[154:157], v[186:189], v[46:49]
	v_mfma_f32_16x16x32_bf16 v[38:41], v[146:149], v[202:205], v[38:41]
	v_mfma_f32_16x16x32_bf16 v[30:33], v[154:157], v[202:205], v[30:33]
	v_mfma_f32_16x16x32_bf16 v[22:25], v[146:149], v[220:223], v[22:25]
	v_mfma_f32_16x16x32_bf16 v[14:17], v[154:157], v[220:223], v[14:17]
	v_mfma_f32_16x16x32_bf16 v[62:65], v[150:153], v[182:185], v[62:65]
	v_mfma_f32_16x16x32_bf16 v[58:61], v[158:161], v[182:185], v[58:61]
	v_mfma_f32_16x16x32_bf16 v[54:57], v[150:153], v[190:193], v[54:57]
	v_mfma_f32_16x16x32_bf16 v[46:49], v[158:161], v[190:193], v[46:49]
	v_mfma_f32_16x16x32_bf16 v[38:41], v[150:153], v[206:209], v[38:41]
	v_mfma_f32_16x16x32_bf16 v[30:33], v[158:161], v[206:209], v[30:33]
	v_mfma_f32_16x16x32_bf16 v[22:25], v[150:153], v[224:227], v[22:25]
	v_mfma_f32_16x16x32_bf16 v[14:17], v[158:161], v[224:227], v[14:17]
	v_mfma_f32_16x16x32_bf16 v[50:53], v[162:165], v[178:181], v[50:53]
	v_mfma_f32_16x16x32_bf16 v[42:45], v[170:173], v[178:181], v[42:45]
	v_mfma_f32_16x16x32_bf16 v[34:37], v[162:165], v[186:189], v[34:37]
	v_mfma_f32_16x16x32_bf16 v[26:29], v[170:173], v[186:189], v[26:29]
	v_mfma_f32_16x16x32_bf16 v[18:21], v[162:165], v[202:205], v[18:21]
	v_mfma_f32_16x16x32_bf16 v[10:13], v[170:173], v[202:205], v[10:13]
	v_mfma_f32_16x16x32_bf16 v[6:9], v[162:165], v[220:223], v[6:9]
	v_mfma_f32_16x16x32_bf16 v[2:5], v[170:173], v[220:223], v[2:5]
	v_mfma_f32_16x16x32_bf16 v[50:53], v[166:169], v[182:185], v[50:53]
	v_mfma_f32_16x16x32_bf16 v[42:45], v[174:177], v[182:185], v[42:45]
	v_mfma_f32_16x16x32_bf16 v[34:37], v[166:169], v[190:193], v[34:37]
	v_mfma_f32_16x16x32_bf16 v[26:29], v[174:177], v[190:193], v[26:29]
	v_mfma_f32_16x16x32_bf16 v[18:21], v[166:169], v[206:209], v[18:21]
	v_mfma_f32_16x16x32_bf16 v[10:13], v[174:177], v[206:209], v[10:13]
	v_mfma_f32_16x16x32_bf16 v[6:9], v[166:169], v[224:227], v[6:9]
	v_mfma_f32_16x16x32_bf16 v[2:5], v[174:177], v[224:227], v[2:5]
	s_barrier
	s_add_u32 vcc_lo, vcc_lo, 0x100
	s_addc_u32 vcc_hi, vcc_hi, 0
	s_add_u32 s82, s82, 0x100
	s_addc_u32 s83, s83, 0
	s_cmp_ge_u32 s72, s66
	s_mov_b32 s42, s72
	s_cbranch_scc1 .Lpeel_exit_bf
.LBB0_308:
	s_add_i32 s72, s42, 2
	s_add_u32 s73, vcc_lo, 0x80
	s_addc_u32 s43, vcc_hi, 0
	s_add_i32 s45, 0, 0x10000
	s_cmp_eq_u32 s63, s42
	s_cselect_b32 s43, s9, s43
	s_cselect_b32 s42, s8, s73
	v_add_u32_e32 v140, s45, v143
	s_cselect_b32 s75, s91, s83
	s_cselect_b32 s74, s90, s82
	s_add_i32 s73, 0, 0x14000
	ds_read_b128 v[146:149], v140
	ds_read_b128 v[150:153], v140 offset:1024
	ds_read_b128 v[154:157], v140 offset:2048
	ds_read_b128 v[158:161], v140 offset:3072
	v_add_u32_e32 v140, s73, v143
	ds_read_b128 v[162:165], v140
	ds_read_b128 v[166:169], v140 offset:1024
	ds_read_b128 v[170:173], v140 offset:2048
	ds_read_b128 v[174:177], v140 offset:3072
	v_lshl_add_u64 v[140:141], vcc, 0, v[136:137]
	s_add_i32 m0, s59, 0xc000
	ds_read_b128 v[178:181], v145
	ds_read_b128 v[182:185], v145 offset:1024
	ds_read_b128 v[186:189], v145 offset:2048
	ds_read_b128 v[190:193], v145 offset:3072
	ds_read_b128 v[202:205], v145 offset:4096
	ds_read_b128 v[206:209], v145 offset:5120
	ds_read_b128 v[220:223], v145 offset:6144
	ds_read_b128 v[224:227], v145 offset:7168
	global_load_lds_dwordx4 v[140:141], off
	v_lshl_add_u64 v[140:141], vcc, 0, v[138:139]
	s_add_i32 m0, s59, 0xe000
	s_nop 0
	global_load_lds_dwordx4 v[140:141], off
	s_waitcnt vmcnt(8)
	s_waitcnt lgkmcnt(0)
	s_barrier
	s_waitcnt lgkmcnt(0)
	v_mfma_f32_16x16x32_bf16 v[126:129], v[146:149], v[178:181], v[126:129]
	v_mfma_f32_16x16x32_bf16 v[122:125], v[154:157], v[178:181], v[122:125]
	v_mfma_f32_16x16x32_bf16 v[118:121], v[146:149], v[186:189], v[118:121]
	v_mfma_f32_16x16x32_bf16 v[110:113], v[154:157], v[186:189], v[110:113]
	v_mfma_f32_16x16x32_bf16 v[102:105], v[146:149], v[202:205], v[102:105]
	v_mfma_f32_16x16x32_bf16 v[94:97], v[154:157], v[202:205], v[94:97]
	v_mfma_f32_16x16x32_bf16 v[86:89], v[146:149], v[220:223], v[86:89]
	v_mfma_f32_16x16x32_bf16 v[78:81], v[154:157], v[220:223], v[78:81]
	v_mfma_f32_16x16x32_bf16 v[126:129], v[150:153], v[182:185], v[126:129]
	v_mfma_f32_16x16x32_bf16 v[122:125], v[158:161], v[182:185], v[122:125]
	v_mfma_f32_16x16x32_bf16 v[118:121], v[150:153], v[190:193], v[118:121]
	v_mfma_f32_16x16x32_bf16 v[110:113], v[158:161], v[190:193], v[110:113]
	v_mfma_f32_16x16x32_bf16 v[102:105], v[150:153], v[206:209], v[102:105]
	v_mfma_f32_16x16x32_bf16 v[94:97], v[158:161], v[206:209], v[94:97]
	v_mfma_f32_16x16x32_bf16 v[86:89], v[150:153], v[224:227], v[86:89]
	v_mfma_f32_16x16x32_bf16 v[78:81], v[158:161], v[224:227], v[78:81]
	v_mfma_f32_16x16x32_bf16 v[114:117], v[162:165], v[178:181], v[114:117]
	v_mfma_f32_16x16x32_bf16 v[106:109], v[170:173], v[178:181], v[106:109]
	v_mfma_f32_16x16x32_bf16 v[98:101], v[162:165], v[186:189], v[98:101]
	v_mfma_f32_16x16x32_bf16 v[90:93], v[170:173], v[186:189], v[90:93]
	v_mfma_f32_16x16x32_bf16 v[82:85], v[162:165], v[202:205], v[82:85]
	v_mfma_f32_16x16x32_bf16 v[74:77], v[170:173], v[202:205], v[74:77]
	v_mfma_f32_16x16x32_bf16 v[70:73], v[162:165], v[220:223], v[70:73]
	v_mfma_f32_16x16x32_bf16 v[66:69], v[170:173], v[220:223], v[66:69]
	v_mfma_f32_16x16x32_bf16 v[114:117], v[166:169], v[182:185], v[114:117]
	v_mfma_f32_16x16x32_bf16 v[106:109], v[174:177], v[182:185], v[106:109]
	v_mfma_f32_16x16x32_bf16 v[98:101], v[166:169], v[190:193], v[98:101]
	v_mfma_f32_16x16x32_bf16 v[90:93], v[174:177], v[190:193], v[90:93]
	v_mfma_f32_16x16x32_bf16 v[82:85], v[166:169], v[206:209], v[82:85]
	v_mfma_f32_16x16x32_bf16 v[74:77], v[174:177], v[206:209], v[74:77]
	v_mfma_f32_16x16x32_bf16 v[70:73], v[166:169], v[224:227], v[70:73]
	v_mfma_f32_16x16x32_bf16 v[66:69], v[174:177], v[224:227], v[66:69]
	s_barrier
	s_add_i32 s45, s45, s54
	v_lshl_add_u64 v[140:141], s[74:75], 0, v[0:1]
	s_mov_b32 m0, s45
	ds_read_b128 v[178:181], v145 offset:16384
	ds_read_b128 v[182:185], v145 offset:17408
	ds_read_b128 v[186:189], v145 offset:18432
	ds_read_b128 v[190:193], v145 offset:19456
	ds_read_b128 v[202:205], v145 offset:20480
	ds_read_b128 v[206:209], v145 offset:21504
	ds_read_b128 v[220:223], v145 offset:22528
	ds_read_b128 v[224:227], v145 offset:23552
	global_load_lds_dwordx4 v[140:141], off
	s_add_i32 m0, s45, 0x2000
	v_lshl_add_u64 v[194:195], s[74:75], 0, v[134:135]
	s_add_u32 s74, s74, s80
	s_addc_u32 s75, s75, 0
	s_add_i32 s45, s73, s54
	global_load_lds_dwordx4 v[194:195], off
	v_lshl_add_u64 v[198:199], s[74:75], 0, v[0:1]
	s_mov_b32 m0, s45
	v_lshl_add_u64 v[200:201], s[74:75], 0, v[134:135]
	global_load_lds_dwordx4 v[198:199], off
	s_add_i32 m0, s45, 0x2000
	v_lshl_add_u64 v[210:211], s[42:43], 0, v[130:131]
	global_load_lds_dwordx4 v[200:201], off
	s_mov_b32 m0, s59
	v_lshl_add_u64 v[212:213], s[42:43], 0, v[132:133]
	global_load_lds_dwordx4 v[210:211], off
	s_mov_b32 m0, s60
	s_nop 0
	global_load_lds_dwordx4 v[212:213], off
	s_waitcnt vmcnt(8)
	s_waitcnt lgkmcnt(0)
	s_barrier
	s_waitcnt lgkmcnt(0)
	v_mfma_f32_16x16x32_bf16 v[62:65], v[146:149], v[178:181], v[62:65]
	v_mfma_f32_16x16x32_bf16 v[58:61], v[154:157], v[178:181], v[58:61]
	v_mfma_f32_16x16x32_bf16 v[54:57], v[146:149], v[186:189], v[54:57]
	v_mfma_f32_16x16x32_bf16 v[46:49], v[154:157], v[186:189], v[46:49]
	v_mfma_f32_16x16x32_bf16 v[38:41], v[146:149], v[202:205], v[38:41]
	v_mfma_f32_16x16x32_bf16 v[30:33], v[154:157], v[202:205], v[30:33]
	v_mfma_f32_16x16x32_bf16 v[22:25], v[146:149], v[220:223], v[22:25]
	v_mfma_f32_16x16x32_bf16 v[14:17], v[154:157], v[220:223], v[14:17]
	v_mfma_f32_16x16x32_bf16 v[62:65], v[150:153], v[182:185], v[62:65]
	v_mfma_f32_16x16x32_bf16 v[58:61], v[158:161], v[182:185], v[58:61]
	v_mfma_f32_16x16x32_bf16 v[54:57], v[150:153], v[190:193], v[54:57]
	v_mfma_f32_16x16x32_bf16 v[46:49], v[158:161], v[190:193], v[46:49]
	v_mfma_f32_16x16x32_bf16 v[38:41], v[150:153], v[206:209], v[38:41]
	v_mfma_f32_16x16x32_bf16 v[30:33], v[158:161], v[206:209], v[30:33]
	v_mfma_f32_16x16x32_bf16 v[22:25], v[150:153], v[224:227], v[22:25]
	v_mfma_f32_16x16x32_bf16 v[14:17], v[158:161], v[224:227], v[14:17]
	v_mfma_f32_16x16x32_bf16 v[50:53], v[162:165], v[178:181], v[50:53]
	v_mfma_f32_16x16x32_bf16 v[42:45], v[170:173], v[178:181], v[42:45]
	v_mfma_f32_16x16x32_bf16 v[34:37], v[162:165], v[186:189], v[34:37]
	v_mfma_f32_16x16x32_bf16 v[26:29], v[170:173], v[186:189], v[26:29]
	v_mfma_f32_16x16x32_bf16 v[18:21], v[162:165], v[202:205], v[18:21]
	v_mfma_f32_16x16x32_bf16 v[10:13], v[170:173], v[202:205], v[10:13]
	v_mfma_f32_16x16x32_bf16 v[6:9], v[162:165], v[220:223], v[6:9]
	v_mfma_f32_16x16x32_bf16 v[2:5], v[170:173], v[220:223], v[2:5]
	v_mfma_f32_16x16x32_bf16 v[50:53], v[166:169], v[182:185], v[50:53]
	v_mfma_f32_16x16x32_bf16 v[42:45], v[174:177], v[182:185], v[42:45]
	v_mfma_f32_16x16x32_bf16 v[34:37], v[166:169], v[190:193], v[34:37]
	v_mfma_f32_16x16x32_bf16 v[26:29], v[174:177], v[190:193], v[26:29]
	v_mfma_f32_16x16x32_bf16 v[18:21], v[166:169], v[206:209], v[18:21]
	v_mfma_f32_16x16x32_bf16 v[10:13], v[174:177], v[206:209], v[10:13]
	v_mfma_f32_16x16x32_bf16 v[6:9], v[166:169], v[224:227], v[6:9]
	v_mfma_f32_16x16x32_bf16 v[2:5], v[174:177], v[224:227], v[2:5]
	s_barrier
	s_add_i32 s45, 0, 0x18000
	s_add_i32 s73, 0, 0x1c000
	v_add_u32_e32 v158, s45, v143
	v_add_u32_e32 v174, s73, v143
	ds_read_b128 v[146:149], v158
	ds_read_b128 v[150:153], v158 offset:1024
	ds_read_b128 v[154:157], v158 offset:2048
	ds_read_b128 v[158:161], v158 offset:3072
	ds_read_b128 v[162:165], v174
	ds_read_b128 v[166:169], v174 offset:1024
	ds_read_b128 v[170:173], v174 offset:2048
	ds_read_b128 v[174:177], v174 offset:3072
	s_add_u32 s42, s42, s80
	s_addc_u32 s43, s43, 0
	s_mov_b32 m0, s61
	v_lshl_add_u64 v[214:215], s[42:43], 0, v[130:131]
	ds_read_b128 v[178:181], v145 offset:32768
	ds_read_b128 v[182:185], v145 offset:33792
	ds_read_b128 v[186:189], v145 offset:34816
	ds_read_b128 v[190:193], v145 offset:35840
	ds_read_b128 v[202:205], v145 offset:36864
	ds_read_b128 v[206:209], v145 offset:37888
	ds_read_b128 v[220:223], v145 offset:38912
	ds_read_b128 v[224:227], v145 offset:39936
	global_load_lds_dwordx4 v[214:215], off
	v_lshl_add_u64 v[214:215], s[42:43], 0, v[132:133]
	s_mov_b32 m0, s62
	s_nop 0
	global_load_lds_dwordx4 v[214:215], off
	s_waitcnt vmcnt(8)
	s_waitcnt lgkmcnt(0)
	s_barrier
	s_waitcnt lgkmcnt(0)
	v_mfma_f32_16x16x32_bf16 v[126:129], v[146:149], v[178:181], v[126:129]
	v_mfma_f32_16x16x32_bf16 v[122:125], v[154:157], v[178:181], v[122:125]
	v_mfma_f32_16x16x32_bf16 v[118:121], v[146:149], v[186:189], v[118:121]
	v_mfma_f32_16x16x32_bf16 v[110:113], v[154:157], v[186:189], v[110:113]
	v_mfma_f32_16x16x32_bf16 v[102:105], v[146:149], v[202:205], v[102:105]
	v_mfma_f32_16x16x32_bf16 v[94:97], v[154:157], v[202:205], v[94:97]
	v_mfma_f32_16x16x32_bf16 v[86:89], v[146:149], v[220:223], v[86:89]
	v_mfma_f32_16x16x32_bf16 v[78:81], v[154:157], v[220:223], v[78:81]
	v_mfma_f32_16x16x32_bf16 v[126:129], v[150:153], v[182:185], v[126:129]
	v_mfma_f32_16x16x32_bf16 v[122:125], v[158:161], v[182:185], v[122:125]
	v_mfma_f32_16x16x32_bf16 v[118:121], v[150:153], v[190:193], v[118:121]
	v_mfma_f32_16x16x32_bf16 v[110:113], v[158:161], v[190:193], v[110:113]
	v_mfma_f32_16x16x32_bf16 v[102:105], v[150:153], v[206:209], v[102:105]
	v_mfma_f32_16x16x32_bf16 v[94:97], v[158:161], v[206:209], v[94:97]
	v_mfma_f32_16x16x32_bf16 v[86:89], v[150:153], v[224:227], v[86:89]
	v_mfma_f32_16x16x32_bf16 v[78:81], v[158:161], v[224:227], v[78:81]
	v_mfma_f32_16x16x32_bf16 v[114:117], v[162:165], v[178:181], v[114:117]
	v_mfma_f32_16x16x32_bf16 v[106:109], v[170:173], v[178:181], v[106:109]
	v_mfma_f32_16x16x32_bf16 v[98:101], v[162:165], v[186:189], v[98:101]
	v_mfma_f32_16x16x32_bf16 v[90:93], v[170:173], v[186:189], v[90:93]
	v_mfma_f32_16x16x32_bf16 v[82:85], v[162:165], v[202:205], v[82:85]
	v_mfma_f32_16x16x32_bf16 v[74:77], v[170:173], v[202:205], v[74:77]
	v_mfma_f32_16x16x32_bf16 v[70:73], v[162:165], v[220:223], v[70:73]
	v_mfma_f32_16x16x32_bf16 v[66:69], v[170:173], v[220:223], v[66:69]
	v_mfma_f32_16x16x32_bf16 v[114:117], v[166:169], v[182:185], v[114:117]
	v_mfma_f32_16x16x32_bf16 v[106:109], v[174:177], v[182:185], v[106:109]
	v_mfma_f32_16x16x32_bf16 v[98:101], v[166:169], v[190:193], v[98:101]
	v_mfma_f32_16x16x32_bf16 v[90:93], v[174:177], v[190:193], v[90:93]
	v_mfma_f32_16x16x32_bf16 v[82:85], v[166:169], v[206:209], v[82:85]
	v_mfma_f32_16x16x32_bf16 v[74:77], v[174:177], v[206:209], v[74:77]
	v_mfma_f32_16x16x32_bf16 v[70:73], v[166:169], v[224:227], v[70:73]
	v_mfma_f32_16x16x32_bf16 v[66:69], v[174:177], v[224:227], v[66:69]
	s_barrier
	s_add_i32 s42, s45, s54
	v_lshl_add_u64 v[140:141], v[140:141], 0, s[84:85]
	s_mov_b32 m0, s42
	ds_read_b128 v[178:181], v145 offset:49152
	ds_read_b128 v[182:185], v145 offset:50176
	ds_read_b128 v[186:189], v145 offset:51200
	ds_read_b128 v[190:193], v145 offset:52224
	ds_read_b128 v[202:205], v145 offset:53248
	ds_read_b128 v[206:209], v145 offset:54272
	ds_read_b128 v[220:223], v145 offset:55296
	ds_read_b128 v[224:227], v145 offset:56320
	global_load_lds_dwordx4 v[140:141], off
	v_lshl_add_u64 v[140:141], v[194:195], 0, s[84:85]
	s_add_i32 m0, s42, 0x2000
	s_add_i32 s42, s73, s54
	global_load_lds_dwordx4 v[140:141], off
	v_lshl_add_u64 v[140:141], v[198:199], 0, s[84:85]
	s_mov_b32 m0, s42
	s_nop 0
	global_load_lds_dwordx4 v[140:141], off
	v_lshl_add_u64 v[140:141], v[200:201], 0, s[84:85]
	s_add_i32 m0, s42, 0x2000
	s_nop 0
	global_load_lds_dwordx4 v[140:141], off
	v_lshl_add_u64 v[140:141], v[210:211], 0, s[84:85]
	s_mov_b32 m0, s64
	s_nop 0
	global_load_lds_dwordx4 v[140:141], off
	v_lshl_add_u64 v[140:141], v[212:213], 0, s[84:85]
	s_mov_b32 m0, s65
	s_nop 0
	global_load_lds_dwordx4 v[140:141], off
	s_waitcnt vmcnt(8)
	s_waitcnt lgkmcnt(0)
	s_barrier
	s_waitcnt lgkmcnt(0)
	v_mfma_f32_16x16x32_bf16 v[62:65], v[146:149], v[178:181], v[62:65]
	v_mfma_f32_16x16x32_bf16 v[58:61], v[154:157], v[178:181], v[58:61]
	v_mfma_f32_16x16x32_bf16 v[54:57], v[146:149], v[186:189], v[54:57]
	v_mfma_f32_16x16x32_bf16 v[46:49], v[154:157], v[186:189], v[46:49]
	v_mfma_f32_16x16x32_bf16 v[38:41], v[146:149], v[202:205], v[38:41]
	v_mfma_f32_16x16x32_bf16 v[30:33], v[154:157], v[202:205], v[30:33]
	v_mfma_f32_16x16x32_bf16 v[22:25], v[146:149], v[220:223], v[22:25]
	v_mfma_f32_16x16x32_bf16 v[14:17], v[154:157], v[220:223], v[14:17]
	v_mfma_f32_16x16x32_bf16 v[62:65], v[150:153], v[182:185], v[62:65]
	v_mfma_f32_16x16x32_bf16 v[58:61], v[158:161], v[182:185], v[58:61]
	v_mfma_f32_16x16x32_bf16 v[54:57], v[150:153], v[190:193], v[54:57]
	v_mfma_f32_16x16x32_bf16 v[46:49], v[158:161], v[190:193], v[46:49]
	v_mfma_f32_16x16x32_bf16 v[38:41], v[150:153], v[206:209], v[38:41]
	v_mfma_f32_16x16x32_bf16 v[30:33], v[158:161], v[206:209], v[30:33]
	v_mfma_f32_16x16x32_bf16 v[22:25], v[150:153], v[224:227], v[22:25]
	v_mfma_f32_16x16x32_bf16 v[14:17], v[158:161], v[224:227], v[14:17]
	v_mfma_f32_16x16x32_bf16 v[50:53], v[162:165], v[178:181], v[50:53]
	v_mfma_f32_16x16x32_bf16 v[42:45], v[170:173], v[178:181], v[42:45]
	v_mfma_f32_16x16x32_bf16 v[34:37], v[162:165], v[186:189], v[34:37]
	v_mfma_f32_16x16x32_bf16 v[26:29], v[170:173], v[186:189], v[26:29]
	v_mfma_f32_16x16x32_bf16 v[18:21], v[162:165], v[202:205], v[18:21]
	v_mfma_f32_16x16x32_bf16 v[10:13], v[170:173], v[202:205], v[10:13]
	v_mfma_f32_16x16x32_bf16 v[6:9], v[162:165], v[220:223], v[6:9]
	v_mfma_f32_16x16x32_bf16 v[2:5], v[170:173], v[220:223], v[2:5]
	v_mfma_f32_16x16x32_bf16 v[50:53], v[166:169], v[182:185], v[50:53]
	v_mfma_f32_16x16x32_bf16 v[42:45], v[174:177], v[182:185], v[42:45]
	v_mfma_f32_16x16x32_bf16 v[34:37], v[166:169], v[190:193], v[34:37]
	v_mfma_f32_16x16x32_bf16 v[26:29], v[174:177], v[190:193], v[26:29]
	v_mfma_f32_16x16x32_bf16 v[18:21], v[166:169], v[206:209], v[18:21]
	v_mfma_f32_16x16x32_bf16 v[10:13], v[174:177], v[206:209], v[10:13]
	v_mfma_f32_16x16x32_bf16 v[6:9], v[166:169], v[224:227], v[6:9]
	v_mfma_f32_16x16x32_bf16 v[2:5], v[174:177], v[224:227], v[2:5]
	s_barrier
	s_add_u32 vcc_lo, vcc_lo, 0x100
	s_addc_u32 vcc_hi, vcc_hi, 0
	s_add_u32 s82, s82, 0x100
	s_addc_u32 s83, s83, 0
	s_cmp_ge_u32 s72, s66
	s_mov_b32 s42, s72
	s_cbranch_scc0 .LBB0_308

.LBB0_351:
	s_add_u32 s8, s76, 0x80
	s_addc_u32 s9, s77, 0
	s_add_u32 s59, s36, 0x100
	s_addc_u32 s60, s37, 0
	s_mov_b32 s36, 0
	s_add_i32 s61, s36, 2
	s_add_u32 s45, s8, 0x80
	s_addc_u32 s37, s9, 0
	s_add_i32 s64, 0, 0x10000
	s_cmp_eq_u32 s48, s36
	s_cselect_b32 s37, s39, s37
	s_cselect_b32 s36, s38, s45
	s_cselect_b32 s63, s41, s60
	s_cselect_b32 s62, s40, s59
	s_add_i32 s45, 0, 0x14000
	v_add_u32_e32 v158, s64, v148
	v_add_u32_e32 v174, s45, v148
	ds_read_b128 v[144:147], v158
	ds_read_b128 v[150:153], v158 offset:1024
	ds_read_b128 v[154:157], v158 offset:2048
	ds_read_b128 v[158:161], v158 offset:3072
	ds_read_b128 v[162:165], v174
	ds_read_b128 v[166:169], v174 offset:1024
	ds_read_b128 v[170:173], v174 offset:2048
	ds_read_b128 v[174:177], v174 offset:3072
	v_lshl_add_u64 v[194:195], s[8:9], 0, v[140:141]
	s_add_i32 m0, s82, 0xc000
	ds_read_b128 v[178:181], v149
	ds_read_b128 v[182:185], v149 offset:1024
	ds_read_b128 v[186:189], v149 offset:2048
	ds_read_b128 v[190:193], v149 offset:3072
	ds_read_b128 v[202:205], v149 offset:4096
	ds_read_b128 v[206:209], v149 offset:5120
	ds_read_b128 v[220:223], v149 offset:6144
	ds_read_b128 v[224:227], v149 offset:7168
	global_load_lds_dwordx4 v[194:195], off
	v_lshl_add_u64 v[194:195], s[8:9], 0, v[142:143]
	s_add_i32 m0, s82, 0xe000
	s_nop 0
	global_load_lds_dwordx4 v[194:195], off
	s_waitcnt vmcnt(8)
	s_waitcnt lgkmcnt(0)
	s_barrier
	s_waitcnt lgkmcnt(0)
	v_mfma_f32_16x16x32_bf16 v[126:129], v[144:147], v[178:181], 0
	v_mfma_f32_16x16x32_bf16 v[122:125], v[154:157], v[178:181], 0
	v_mfma_f32_16x16x32_bf16 v[110:113], v[144:147], v[186:189], 0
	v_mfma_f32_16x16x32_bf16 v[106:109], v[154:157], v[186:189], 0
	v_mfma_f32_16x16x32_bf16 v[94:97], v[144:147], v[202:205], 0
	v_mfma_f32_16x16x32_bf16 v[90:93], v[154:157], v[202:205], 0
	v_mfma_f32_16x16x32_bf16 v[78:81], v[144:147], v[220:223], 0
	v_mfma_f32_16x16x32_bf16 v[74:77], v[154:157], v[220:223], 0
	v_mfma_f32_16x16x32_bf16 v[126:129], v[150:153], v[182:185], v[126:129]
	v_mfma_f32_16x16x32_bf16 v[122:125], v[158:161], v[182:185], v[122:125]
	v_mfma_f32_16x16x32_bf16 v[110:113], v[150:153], v[190:193], v[110:113]
	v_mfma_f32_16x16x32_bf16 v[106:109], v[158:161], v[190:193], v[106:109]
	v_mfma_f32_16x16x32_bf16 v[94:97], v[150:153], v[206:209], v[94:97]
	v_mfma_f32_16x16x32_bf16 v[90:93], v[158:161], v[206:209], v[90:93]
	v_mfma_f32_16x16x32_bf16 v[78:81], v[150:153], v[224:227], v[78:81]
	v_mfma_f32_16x16x32_bf16 v[74:77], v[158:161], v[224:227], v[74:77]
	v_mfma_f32_16x16x32_bf16 v[118:121], v[162:165], v[178:181], 0
	v_mfma_f32_16x16x32_bf16 v[114:117], v[170:173], v[178:181], 0
	v_mfma_f32_16x16x32_bf16 v[102:105], v[162:165], v[186:189], 0
	v_mfma_f32_16x16x32_bf16 v[98:101], v[170:173], v[186:189], 0
	v_mfma_f32_16x16x32_bf16 v[86:89], v[162:165], v[202:205], 0
	v_mfma_f32_16x16x32_bf16 v[82:85], v[170:173], v[202:205], 0
	v_mfma_f32_16x16x32_bf16 v[70:73], v[162:165], v[220:223], 0
	v_mfma_f32_16x16x32_bf16 v[66:69], v[170:173], v[220:223], 0
	v_mfma_f32_16x16x32_bf16 v[118:121], v[166:169], v[182:185], v[118:121]
	v_mfma_f32_16x16x32_bf16 v[114:117], v[174:177], v[182:185], v[114:117]
	v_mfma_f32_16x16x32_bf16 v[102:105], v[166:169], v[190:193], v[102:105]
	v_mfma_f32_16x16x32_bf16 v[98:101], v[174:177], v[190:193], v[98:101]
	v_mfma_f32_16x16x32_bf16 v[86:89], v[166:169], v[206:209], v[86:89]
	v_mfma_f32_16x16x32_bf16 v[82:85], v[174:177], v[206:209], v[82:85]
	v_mfma_f32_16x16x32_bf16 v[70:73], v[166:169], v[224:227], v[70:73]
	v_mfma_f32_16x16x32_bf16 v[66:69], v[174:177], v[224:227], v[66:69]
	s_barrier
	s_add_i32 s64, s64, s79
	v_lshl_add_u64 v[194:195], s[62:63], 0, v[132:133]
	s_mov_b32 m0, s64
	ds_read_b128 v[178:181], v149 offset:16384
	ds_read_b128 v[182:185], v149 offset:17408
	ds_read_b128 v[186:189], v149 offset:18432
	ds_read_b128 v[190:193], v149 offset:19456
	ds_read_b128 v[202:205], v149 offset:20480
	ds_read_b128 v[206:209], v149 offset:21504
	ds_read_b128 v[220:223], v149 offset:22528
	ds_read_b128 v[224:227], v149 offset:23552
	global_load_lds_dwordx4 v[194:195], off
	s_add_i32 m0, s64, 0x2000
	v_lshl_add_u64 v[198:199], s[62:63], 0, v[136:137]
	s_add_u32 s62, s62, s80
	s_addc_u32 s63, s63, 0
	s_add_i32 s45, s45, s79
	global_load_lds_dwordx4 v[198:199], off
	v_lshl_add_u64 v[200:201], s[62:63], 0, v[132:133]
	s_mov_b32 m0, s45
	v_lshl_add_u64 v[210:211], s[62:63], 0, v[136:137]
	global_load_lds_dwordx4 v[200:201], off
	s_add_i32 m0, s45, 0x2000
	v_lshl_add_u64 v[212:213], s[36:37], 0, v[130:131]
	global_load_lds_dwordx4 v[210:211], off
	s_mov_b32 m0, s82
	v_lshl_add_u64 v[214:215], s[36:37], 0, v[134:135]
	global_load_lds_dwordx4 v[212:213], off
	s_mov_b32 m0, s83
	s_nop 0
	global_load_lds_dwordx4 v[214:215], off
	s_waitcnt vmcnt(8)
	s_waitcnt lgkmcnt(0)
	s_barrier
	s_waitcnt lgkmcnt(0)
	v_mfma_f32_16x16x32_bf16 v[62:65], v[144:147], v[178:181], 0
	v_mfma_f32_16x16x32_bf16 v[58:61], v[154:157], v[178:181], 0
	v_mfma_f32_16x16x32_bf16 v[46:49], v[144:147], v[186:189], 0
	v_mfma_f32_16x16x32_bf16 v[42:45], v[154:157], v[186:189], 0
	v_mfma_f32_16x16x32_bf16 v[30:33], v[144:147], v[202:205], 0
	v_mfma_f32_16x16x32_bf16 v[26:29], v[154:157], v[202:205], 0
	v_mfma_f32_16x16x32_bf16 v[14:17], v[144:147], v[220:223], 0
	v_mfma_f32_16x16x32_bf16 v[10:13], v[154:157], v[220:223], 0
	v_mfma_f32_16x16x32_bf16 v[62:65], v[150:153], v[182:185], v[62:65]
	v_mfma_f32_16x16x32_bf16 v[58:61], v[158:161], v[182:185], v[58:61]
	v_mfma_f32_16x16x32_bf16 v[46:49], v[150:153], v[190:193], v[46:49]
	v_mfma_f32_16x16x32_bf16 v[42:45], v[158:161], v[190:193], v[42:45]
	v_mfma_f32_16x16x32_bf16 v[30:33], v[150:153], v[206:209], v[30:33]
	v_mfma_f32_16x16x32_bf16 v[26:29], v[158:161], v[206:209], v[26:29]
	v_mfma_f32_16x16x32_bf16 v[14:17], v[150:153], v[224:227], v[14:17]
	v_mfma_f32_16x16x32_bf16 v[10:13], v[158:161], v[224:227], v[10:13]
	v_mfma_f32_16x16x32_bf16 v[54:57], v[162:165], v[178:181], 0
	v_mfma_f32_16x16x32_bf16 v[50:53], v[170:173], v[178:181], 0
	v_mfma_f32_16x16x32_bf16 v[38:41], v[162:165], v[186:189], 0
	v_mfma_f32_16x16x32_bf16 v[34:37], v[170:173], v[186:189], 0
	v_mfma_f32_16x16x32_bf16 v[22:25], v[162:165], v[202:205], 0
	v_mfma_f32_16x16x32_bf16 v[18:21], v[170:173], v[202:205], 0
	v_mfma_f32_16x16x32_bf16 v[6:9], v[162:165], v[220:223], 0
	v_mfma_f32_16x16x32_bf16 v[2:5], v[170:173], v[220:223], 0
	v_mfma_f32_16x16x32_bf16 v[54:57], v[166:169], v[182:185], v[54:57]
	v_mfma_f32_16x16x32_bf16 v[50:53], v[174:177], v[182:185], v[50:53]
	v_mfma_f32_16x16x32_bf16 v[38:41], v[166:169], v[190:193], v[38:41]
	v_mfma_f32_16x16x32_bf16 v[34:37], v[174:177], v[190:193], v[34:37]
	v_mfma_f32_16x16x32_bf16 v[22:25], v[166:169], v[206:209], v[22:25]
	v_mfma_f32_16x16x32_bf16 v[18:21], v[174:177], v[206:209], v[18:21]
	v_mfma_f32_16x16x32_bf16 v[6:9], v[166:169], v[224:227], v[6:9]
	v_mfma_f32_16x16x32_bf16 v[2:5], v[174:177], v[224:227], v[2:5]
	s_barrier
	s_add_i32 s45, 0, 0x18000
	s_add_i32 s62, 0, 0x1c000
	v_add_u32_e32 v158, s45, v148
	v_add_u32_e32 v174, s62, v148
	ds_read_b128 v[144:147], v158
	ds_read_b128 v[150:153], v158 offset:1024
	ds_read_b128 v[154:157], v158 offset:2048
	ds_read_b128 v[158:161], v158 offset:3072
	ds_read_b128 v[162:165], v174
	ds_read_b128 v[166:169], v174 offset:1024
	ds_read_b128 v[170:173], v174 offset:2048
	ds_read_b128 v[174:177], v174 offset:3072
	s_add_u32 s36, s36, s80
	s_addc_u32 s37, s37, 0
	s_mov_b32 m0, s86
	v_lshl_add_u64 v[216:217], s[36:37], 0, v[130:131]
	ds_read_b128 v[178:181], v149 offset:32768
	ds_read_b128 v[182:185], v149 offset:33792
	ds_read_b128 v[186:189], v149 offset:34816
	ds_read_b128 v[190:193], v149 offset:35840
	ds_read_b128 v[202:205], v149 offset:36864
	ds_read_b128 v[206:209], v149 offset:37888
	ds_read_b128 v[220:223], v149 offset:38912
	ds_read_b128 v[224:227], v149 offset:39936
	global_load_lds_dwordx4 v[216:217], off
	v_lshl_add_u64 v[216:217], s[36:37], 0, v[134:135]
	s_mov_b32 m0, s87
	s_nop 0
	global_load_lds_dwordx4 v[216:217], off
	s_waitcnt vmcnt(8)
	s_waitcnt lgkmcnt(0)
	s_barrier
	s_waitcnt lgkmcnt(0)
	v_mfma_f32_16x16x32_bf16 v[126:129], v[144:147], v[178:181], v[126:129]
	v_mfma_f32_16x16x32_bf16 v[122:125], v[154:157], v[178:181], v[122:125]
	v_mfma_f32_16x16x32_bf16 v[110:113], v[144:147], v[186:189], v[110:113]
	v_mfma_f32_16x16x32_bf16 v[106:109], v[154:157], v[186:189], v[106:109]
	v_mfma_f32_16x16x32_bf16 v[94:97], v[144:147], v[202:205], v[94:97]
	v_mfma_f32_16x16x32_bf16 v[90:93], v[154:157], v[202:205], v[90:93]
	v_mfma_f32_16x16x32_bf16 v[78:81], v[144:147], v[220:223], v[78:81]
	v_mfma_f32_16x16x32_bf16 v[74:77], v[154:157], v[220:223], v[74:77]
	v_mfma_f32_16x16x32_bf16 v[126:129], v[150:153], v[182:185], v[126:129]
	v_mfma_f32_16x16x32_bf16 v[122:125], v[158:161], v[182:185], v[122:125]
	v_mfma_f32_16x16x32_bf16 v[110:113], v[150:153], v[190:193], v[110:113]
	v_mfma_f32_16x16x32_bf16 v[106:109], v[158:161], v[190:193], v[106:109]
	v_mfma_f32_16x16x32_bf16 v[94:97], v[150:153], v[206:209], v[94:97]
	v_mfma_f32_16x16x32_bf16 v[90:93], v[158:161], v[206:209], v[90:93]
	v_mfma_f32_16x16x32_bf16 v[78:81], v[150:153], v[224:227], v[78:81]
	v_mfma_f32_16x16x32_bf16 v[74:77], v[158:161], v[224:227], v[74:77]
	v_mfma_f32_16x16x32_bf16 v[118:121], v[162:165], v[178:181], v[118:121]
	v_mfma_f32_16x16x32_bf16 v[114:117], v[170:173], v[178:181], v[114:117]
	v_mfma_f32_16x16x32_bf16 v[102:105], v[162:165], v[186:189], v[102:105]
	v_mfma_f32_16x16x32_bf16 v[98:101], v[170:173], v[186:189], v[98:101]
	v_mfma_f32_16x16x32_bf16 v[86:89], v[162:165], v[202:205], v[86:89]
	v_mfma_f32_16x16x32_bf16 v[82:85], v[170:173], v[202:205], v[82:85]
	v_mfma_f32_16x16x32_bf16 v[70:73], v[162:165], v[220:223], v[70:73]
	v_mfma_f32_16x16x32_bf16 v[66:69], v[170:173], v[220:223], v[66:69]
	v_mfma_f32_16x16x32_bf16 v[118:121], v[166:169], v[182:185], v[118:121]
	v_mfma_f32_16x16x32_bf16 v[114:117], v[174:177], v[182:185], v[114:117]
	v_mfma_f32_16x16x32_bf16 v[102:105], v[166:169], v[190:193], v[102:105]
	v_mfma_f32_16x16x32_bf16 v[98:101], v[174:177], v[190:193], v[98:101]
	v_mfma_f32_16x16x32_bf16 v[86:89], v[166:169], v[206:209], v[86:89]
	v_mfma_f32_16x16x32_bf16 v[82:85], v[174:177], v[206:209], v[82:85]
	v_mfma_f32_16x16x32_bf16 v[70:73], v[166:169], v[224:227], v[70:73]
	v_mfma_f32_16x16x32_bf16 v[66:69], v[174:177], v[224:227], v[66:69]
	s_barrier
	s_add_i32 s36, s45, s79
	v_lshl_add_u64 v[194:195], v[194:195], 0, s[84:85]
	s_mov_b32 m0, s36
	ds_read_b128 v[178:181], v149 offset:49152
	ds_read_b128 v[182:185], v149 offset:50176
	ds_read_b128 v[186:189], v149 offset:51200
	ds_read_b128 v[190:193], v149 offset:52224
	ds_read_b128 v[202:205], v149 offset:53248
	ds_read_b128 v[206:209], v149 offset:54272
	ds_read_b128 v[220:223], v149 offset:55296
	ds_read_b128 v[224:227], v149 offset:56320
	global_load_lds_dwordx4 v[194:195], off
	v_lshl_add_u64 v[194:195], v[198:199], 0, s[84:85]
	s_add_i32 m0, s36, 0x2000
	s_add_i32 s36, s62, s79
	global_load_lds_dwordx4 v[194:195], off
	v_lshl_add_u64 v[194:195], v[200:201], 0, s[84:85]
	s_mov_b32 m0, s36
	s_nop 0
	global_load_lds_dwordx4 v[194:195], off
	v_lshl_add_u64 v[194:195], v[210:211], 0, s[84:85]
	s_add_i32 m0, s36, 0x2000
	s_nop 0
	global_load_lds_dwordx4 v[194:195], off
	v_lshl_add_u64 v[194:195], v[212:213], 0, s[84:85]
	s_mov_b32 m0, s46
	s_nop 0
	global_load_lds_dwordx4 v[194:195], off
	v_lshl_add_u64 v[194:195], v[214:215], 0, s[84:85]
	s_mov_b32 m0, s47
	s_nop 0
	global_load_lds_dwordx4 v[194:195], off
	s_waitcnt vmcnt(8)
	s_waitcnt lgkmcnt(0)
	s_barrier
	s_waitcnt lgkmcnt(0)
	v_mfma_f32_16x16x32_bf16 v[62:65], v[144:147], v[178:181], v[62:65]
	v_mfma_f32_16x16x32_bf16 v[58:61], v[154:157], v[178:181], v[58:61]
	v_mfma_f32_16x16x32_bf16 v[46:49], v[144:147], v[186:189], v[46:49]
	v_mfma_f32_16x16x32_bf16 v[42:45], v[154:157], v[186:189], v[42:45]
	v_mfma_f32_16x16x32_bf16 v[30:33], v[144:147], v[202:205], v[30:33]
	v_mfma_f32_16x16x32_bf16 v[26:29], v[154:157], v[202:205], v[26:29]
	v_mfma_f32_16x16x32_bf16 v[14:17], v[144:147], v[220:223], v[14:17]
	v_mfma_f32_16x16x32_bf16 v[10:13], v[154:157], v[220:223], v[10:13]
	v_mfma_f32_16x16x32_bf16 v[62:65], v[150:153], v[182:185], v[62:65]
	v_mfma_f32_16x16x32_bf16 v[58:61], v[158:161], v[182:185], v[58:61]
	v_mfma_f32_16x16x32_bf16 v[46:49], v[150:153], v[190:193], v[46:49]
	v_mfma_f32_16x16x32_bf16 v[42:45], v[158:161], v[190:193], v[42:45]
	v_mfma_f32_16x16x32_bf16 v[30:33], v[150:153], v[206:209], v[30:33]
	v_mfma_f32_16x16x32_bf16 v[26:29], v[158:161], v[206:209], v[26:29]
	v_mfma_f32_16x16x32_bf16 v[14:17], v[150:153], v[224:227], v[14:17]
	v_mfma_f32_16x16x32_bf16 v[10:13], v[158:161], v[224:227], v[10:13]
	v_mfma_f32_16x16x32_bf16 v[54:57], v[162:165], v[178:181], v[54:57]
	v_mfma_f32_16x16x32_bf16 v[50:53], v[170:173], v[178:181], v[50:53]
	v_mfma_f32_16x16x32_bf16 v[38:41], v[162:165], v[186:189], v[38:41]
	v_mfma_f32_16x16x32_bf16 v[34:37], v[170:173], v[186:189], v[34:37]
	v_mfma_f32_16x16x32_bf16 v[22:25], v[162:165], v[202:205], v[22:25]
	v_mfma_f32_16x16x32_bf16 v[18:21], v[170:173], v[202:205], v[18:21]
	v_mfma_f32_16x16x32_bf16 v[6:9], v[162:165], v[220:223], v[6:9]
	v_mfma_f32_16x16x32_bf16 v[2:5], v[170:173], v[220:223], v[2:5]
	v_mfma_f32_16x16x32_bf16 v[54:57], v[166:169], v[182:185], v[54:57]
	v_mfma_f32_16x16x32_bf16 v[50:53], v[174:177], v[182:185], v[50:53]
	v_mfma_f32_16x16x32_bf16 v[38:41], v[166:169], v[190:193], v[38:41]
	v_mfma_f32_16x16x32_bf16 v[34:37], v[174:177], v[190:193], v[34:37]
	v_mfma_f32_16x16x32_bf16 v[22:25], v[166:169], v[206:209], v[22:25]
	v_mfma_f32_16x16x32_bf16 v[18:21], v[174:177], v[206:209], v[18:21]
	v_mfma_f32_16x16x32_bf16 v[6:9], v[166:169], v[224:227], v[6:9]
	v_mfma_f32_16x16x32_bf16 v[2:5], v[174:177], v[224:227], v[2:5]
	s_barrier
	s_add_u32 s8, s8, 0x100
	s_addc_u32 s9, s9, 0
	s_add_u32 s59, s59, 0x100
	s_addc_u32 s60, s60, 0
	s_cmp_ge_u32 s61, s90
	s_mov_b32 s36, s61
	s_cbranch_scc1 .Lpeel_exit_vt
.LBB0_352:
	s_add_i32 s61, s36, 2
	s_add_u32 s45, s8, 0x80
	s_addc_u32 s37, s9, 0
	s_add_i32 s64, 0, 0x10000
	s_cmp_eq_u32 s48, s36
	s_cselect_b32 s37, s39, s37
	s_cselect_b32 s36, s38, s45
	s_cselect_b32 s63, s41, s60
	s_cselect_b32 s62, s40, s59
	s_add_i32 s45, 0, 0x14000
	v_add_u32_e32 v158, s64, v148
	v_add_u32_e32 v174, s45, v148
	ds_read_b128 v[144:147], v158
	ds_read_b128 v[150:153], v158 offset:1024
	ds_read_b128 v[154:157], v158 offset:2048
	ds_read_b128 v[158:161], v158 offset:3072
	ds_read_b128 v[162:165], v174
	ds_read_b128 v[166:169], v174 offset:1024
	ds_read_b128 v[170:173], v174 offset:2048
	ds_read_b128 v[174:177], v174 offset:3072
	v_lshl_add_u64 v[194:195], s[8:9], 0, v[140:141]
	s_add_i32 m0, s82, 0xc000
	ds_read_b128 v[178:181], v149
	ds_read_b128 v[182:185], v149 offset:1024
	ds_read_b128 v[186:189], v149 offset:2048
	ds_read_b128 v[190:193], v149 offset:3072
	ds_read_b128 v[202:205], v149 offset:4096
	ds_read_b128 v[206:209], v149 offset:5120
	ds_read_b128 v[220:223], v149 offset:6144
	ds_read_b128 v[224:227], v149 offset:7168
	global_load_lds_dwordx4 v[194:195], off
	v_lshl_add_u64 v[194:195], s[8:9], 0, v[142:143]
	s_add_i32 m0, s82, 0xe000
	s_nop 0
	global_load_lds_dwordx4 v[194:195], off
	s_waitcnt vmcnt(8)
	s_waitcnt lgkmcnt(0)
	s_barrier
	s_waitcnt lgkmcnt(0)
	v_mfma_f32_16x16x32_bf16 v[126:129], v[144:147], v[178:181], v[126:129]
	v_mfma_f32_16x16x32_bf16 v[122:125], v[154:157], v[178:181], v[122:125]
	v_mfma_f32_16x16x32_bf16 v[110:113], v[144:147], v[186:189], v[110:113]
	v_mfma_f32_16x16x32_bf16 v[106:109], v[154:157], v[186:189], v[106:109]
	v_mfma_f32_16x16x32_bf16 v[94:97], v[144:147], v[202:205], v[94:97]
	v_mfma_f32_16x16x32_bf16 v[90:93], v[154:157], v[202:205], v[90:93]
	v_mfma_f32_16x16x32_bf16 v[78:81], v[144:147], v[220:223], v[78:81]
	v_mfma_f32_16x16x32_bf16 v[74:77], v[154:157], v[220:223], v[74:77]
	v_mfma_f32_16x16x32_bf16 v[126:129], v[150:153], v[182:185], v[126:129]
	v_mfma_f32_16x16x32_bf16 v[122:125], v[158:161], v[182:185], v[122:125]
	v_mfma_f32_16x16x32_bf16 v[110:113], v[150:153], v[190:193], v[110:113]
	v_mfma_f32_16x16x32_bf16 v[106:109], v[158:161], v[190:193], v[106:109]
	v_mfma_f32_16x16x32_bf16 v[94:97], v[150:153], v[206:209], v[94:97]
	v_mfma_f32_16x16x32_bf16 v[90:93], v[158:161], v[206:209], v[90:93]
	v_mfma_f32_16x16x32_bf16 v[78:81], v[150:153], v[224:227], v[78:81]
	v_mfma_f32_16x16x32_bf16 v[74:77], v[158:161], v[224:227], v[74:77]
	v_mfma_f32_16x16x32_bf16 v[118:121], v[162:165], v[178:181], v[118:121]
	v_mfma_f32_16x16x32_bf16 v[114:117], v[170:173], v[178:181], v[114:117]
	v_mfma_f32_16x16x32_bf16 v[102:105], v[162:165], v[186:189], v[102:105]
	v_mfma_f32_16x16x32_bf16 v[98:101], v[170:173], v[186:189], v[98:101]
	v_mfma_f32_16x16x32_bf16 v[86:89], v[162:165], v[202:205], v[86:89]
	v_mfma_f32_16x16x32_bf16 v[82:85], v[170:173], v[202:205], v[82:85]
	v_mfma_f32_16x16x32_bf16 v[70:73], v[162:165], v[220:223], v[70:73]
	v_mfma_f32_16x16x32_bf16 v[66:69], v[170:173], v[220:223], v[66:69]
	v_mfma_f32_16x16x32_bf16 v[118:121], v[166:169], v[182:185], v[118:121]
	v_mfma_f32_16x16x32_bf16 v[114:117], v[174:177], v[182:185], v[114:117]
	v_mfma_f32_16x16x32_bf16 v[102:105], v[166:169], v[190:193], v[102:105]
	v_mfma_f32_16x16x32_bf16 v[98:101], v[174:177], v[190:193], v[98:101]
	v_mfma_f32_16x16x32_bf16 v[86:89], v[166:169], v[206:209], v[86:89]
	v_mfma_f32_16x16x32_bf16 v[82:85], v[174:177], v[206:209], v[82:85]
	v_mfma_f32_16x16x32_bf16 v[70:73], v[166:169], v[224:227], v[70:73]
	v_mfma_f32_16x16x32_bf16 v[66:69], v[174:177], v[224:227], v[66:69]
	s_barrier
	s_add_i32 s64, s64, s79
	v_lshl_add_u64 v[194:195], s[62:63], 0, v[132:133]
	s_mov_b32 m0, s64
	ds_read_b128 v[178:181], v149 offset:16384
	ds_read_b128 v[182:185], v149 offset:17408
	ds_read_b128 v[186:189], v149 offset:18432
	ds_read_b128 v[190:193], v149 offset:19456
	ds_read_b128 v[202:205], v149 offset:20480
	ds_read_b128 v[206:209], v149 offset:21504
	ds_read_b128 v[220:223], v149 offset:22528
	ds_read_b128 v[224:227], v149 offset:23552
	global_load_lds_dwordx4 v[194:195], off
	s_add_i32 m0, s64, 0x2000
	v_lshl_add_u64 v[198:199], s[62:63], 0, v[136:137]
	s_add_u32 s62, s62, s80
	s_addc_u32 s63, s63, 0
	s_add_i32 s45, s45, s79
	global_load_lds_dwordx4 v[198:199], off
	v_lshl_add_u64 v[200:201], s[62:63], 0, v[132:133]
	s_mov_b32 m0, s45
	v_lshl_add_u64 v[210:211], s[62:63], 0, v[136:137]
	global_load_lds_dwordx4 v[200:201], off
	s_add_i32 m0, s45, 0x2000
	v_lshl_add_u64 v[212:213], s[36:37], 0, v[130:131]
	global_load_lds_dwordx4 v[210:211], off
	s_mov_b32 m0, s82
	v_lshl_add_u64 v[214:215], s[36:37], 0, v[134:135]
	global_load_lds_dwordx4 v[212:213], off
	s_mov_b32 m0, s83
	s_nop 0
	global_load_lds_dwordx4 v[214:215], off
	s_waitcnt vmcnt(8)
	s_waitcnt lgkmcnt(0)
	s_barrier
	s_waitcnt lgkmcnt(0)
	v_mfma_f32_16x16x32_bf16 v[62:65], v[144:147], v[178:181], v[62:65]
	v_mfma_f32_16x16x32_bf16 v[58:61], v[154:157], v[178:181], v[58:61]
	v_mfma_f32_16x16x32_bf16 v[46:49], v[144:147], v[186:189], v[46:49]
	v_mfma_f32_16x16x32_bf16 v[42:45], v[154:157], v[186:189], v[42:45]
	v_mfma_f32_16x16x32_bf16 v[30:33], v[144:147], v[202:205], v[30:33]
	v_mfma_f32_16x16x32_bf16 v[26:29], v[154:157], v[202:205], v[26:29]
	v_mfma_f32_16x16x32_bf16 v[14:17], v[144:147], v[220:223], v[14:17]
	v_mfma_f32_16x16x32_bf16 v[10:13], v[154:157], v[220:223], v[10:13]
	v_mfma_f32_16x16x32_bf16 v[62:65], v[150:153], v[182:185], v[62:65]
	v_mfma_f32_16x16x32_bf16 v[58:61], v[158:161], v[182:185], v[58:61]
	v_mfma_f32_16x16x32_bf16 v[46:49], v[150:153], v[190:193], v[46:49]
	v_mfma_f32_16x16x32_bf16 v[42:45], v[158:161], v[190:193], v[42:45]
	v_mfma_f32_16x16x32_bf16 v[30:33], v[150:153], v[206:209], v[30:33]
	v_mfma_f32_16x16x32_bf16 v[26:29], v[158:161], v[206:209], v[26:29]
	v_mfma_f32_16x16x32_bf16 v[14:17], v[150:153], v[224:227], v[14:17]
	v_mfma_f32_16x16x32_bf16 v[10:13], v[158:161], v[224:227], v[10:13]
	v_mfma_f32_16x16x32_bf16 v[54:57], v[162:165], v[178:181], v[54:57]
	v_mfma_f32_16x16x32_bf16 v[50:53], v[170:173], v[178:181], v[50:53]
	v_mfma_f32_16x16x32_bf16 v[38:41], v[162:165], v[186:189], v[38:41]
	v_mfma_f32_16x16x32_bf16 v[34:37], v[170:173], v[186:189], v[34:37]
	v_mfma_f32_16x16x32_bf16 v[22:25], v[162:165], v[202:205], v[22:25]
	v_mfma_f32_16x16x32_bf16 v[18:21], v[170:173], v[202:205], v[18:21]
	v_mfma_f32_16x16x32_bf16 v[6:9], v[162:165], v[220:223], v[6:9]
	v_mfma_f32_16x16x32_bf16 v[2:5], v[170:173], v[220:223], v[2:5]
	v_mfma_f32_16x16x32_bf16 v[54:57], v[166:169], v[182:185], v[54:57]
	v_mfma_f32_16x16x32_bf16 v[50:53], v[174:177], v[182:185], v[50:53]
	v_mfma_f32_16x16x32_bf16 v[38:41], v[166:169], v[190:193], v[38:41]
	v_mfma_f32_16x16x32_bf16 v[34:37], v[174:177], v[190:193], v[34:37]
	v_mfma_f32_16x16x32_bf16 v[22:25], v[166:169], v[206:209], v[22:25]
	v_mfma_f32_16x16x32_bf16 v[18:21], v[174:177], v[206:209], v[18:21]
	v_mfma_f32_16x16x32_bf16 v[6:9], v[166:169], v[224:227], v[6:9]
	v_mfma_f32_16x16x32_bf16 v[2:5], v[174:177], v[224:227], v[2:5]
	s_barrier
	s_add_i32 s45, 0, 0x18000
	s_add_i32 s62, 0, 0x1c000
	v_add_u32_e32 v158, s45, v148
	v_add_u32_e32 v174, s62, v148
	ds_read_b128 v[144:147], v158
	ds_read_b128 v[150:153], v158 offset:1024
	ds_read_b128 v[154:157], v158 offset:2048
	ds_read_b128 v[158:161], v158 offset:3072
	ds_read_b128 v[162:165], v174
	ds_read_b128 v[166:169], v174 offset:1024
	ds_read_b128 v[170:173], v174 offset:2048
	ds_read_b128 v[174:177], v174 offset:3072
	s_add_u32 s36, s36, s80
	s_addc_u32 s37, s37, 0
	s_mov_b32 m0, s86
	v_lshl_add_u64 v[216:217], s[36:37], 0, v[130:131]
	ds_read_b128 v[178:181], v149 offset:32768
	ds_read_b128 v[182:185], v149 offset:33792
	ds_read_b128 v[186:189], v149 offset:34816
	ds_read_b128 v[190:193], v149 offset:35840
	ds_read_b128 v[202:205], v149 offset:36864
	ds_read_b128 v[206:209], v149 offset:37888
	ds_read_b128 v[220:223], v149 offset:38912
	ds_read_b128 v[224:227], v149 offset:39936
	global_load_lds_dwordx4 v[216:217], off
	v_lshl_add_u64 v[216:217], s[36:37], 0, v[134:135]
	s_mov_b32 m0, s87
	s_nop 0
	global_load_lds_dwordx4 v[216:217], off
	s_waitcnt vmcnt(8)
	s_waitcnt lgkmcnt(0)
	s_barrier
	s_waitcnt lgkmcnt(0)
	v_mfma_f32_16x16x32_bf16 v[126:129], v[144:147], v[178:181], v[126:129]
	v_mfma_f32_16x16x32_bf16 v[122:125], v[154:157], v[178:181], v[122:125]
	v_mfma_f32_16x16x32_bf16 v[110:113], v[144:147], v[186:189], v[110:113]
	v_mfma_f32_16x16x32_bf16 v[106:109], v[154:157], v[186:189], v[106:109]
	v_mfma_f32_16x16x32_bf16 v[94:97], v[144:147], v[202:205], v[94:97]
	v_mfma_f32_16x16x32_bf16 v[90:93], v[154:157], v[202:205], v[90:93]
	v_mfma_f32_16x16x32_bf16 v[78:81], v[144:147], v[220:223], v[78:81]
	v_mfma_f32_16x16x32_bf16 v[74:77], v[154:157], v[220:223], v[74:77]
	v_mfma_f32_16x16x32_bf16 v[126:129], v[150:153], v[182:185], v[126:129]
	v_mfma_f32_16x16x32_bf16 v[122:125], v[158:161], v[182:185], v[122:125]
	v_mfma_f32_16x16x32_bf16 v[110:113], v[150:153], v[190:193], v[110:113]
	v_mfma_f32_16x16x32_bf16 v[106:109], v[158:161], v[190:193], v[106:109]
	v_mfma_f32_16x16x32_bf16 v[94:97], v[150:153], v[206:209], v[94:97]
	v_mfma_f32_16x16x32_bf16 v[90:93], v[158:161], v[206:209], v[90:93]
	v_mfma_f32_16x16x32_bf16 v[78:81], v[150:153], v[224:227], v[78:81]
	v_mfma_f32_16x16x32_bf16 v[74:77], v[158:161], v[224:227], v[74:77]
	v_mfma_f32_16x16x32_bf16 v[118:121], v[162:165], v[178:181], v[118:121]
	v_mfma_f32_16x16x32_bf16 v[114:117], v[170:173], v[178:181], v[114:117]
	v_mfma_f32_16x16x32_bf16 v[102:105], v[162:165], v[186:189], v[102:105]
	v_mfma_f32_16x16x32_bf16 v[98:101], v[170:173], v[186:189], v[98:101]
	v_mfma_f32_16x16x32_bf16 v[86:89], v[162:165], v[202:205], v[86:89]
	v_mfma_f32_16x16x32_bf16 v[82:85], v[170:173], v[202:205], v[82:85]
	v_mfma_f32_16x16x32_bf16 v[70:73], v[162:165], v[220:223], v[70:73]
	v_mfma_f32_16x16x32_bf16 v[66:69], v[170:173], v[220:223], v[66:69]
	v_mfma_f32_16x16x32_bf16 v[118:121], v[166:169], v[182:185], v[118:121]
	v_mfma_f32_16x16x32_bf16 v[114:117], v[174:177], v[182:185], v[114:117]
	v_mfma_f32_16x16x32_bf16 v[102:105], v[166:169], v[190:193], v[102:105]
	v_mfma_f32_16x16x32_bf16 v[98:101], v[174:177], v[190:193], v[98:101]
	v_mfma_f32_16x16x32_bf16 v[86:89], v[166:169], v[206:209], v[86:89]
	v_mfma_f32_16x16x32_bf16 v[82:85], v[174:177], v[206:209], v[82:85]
	v_mfma_f32_16x16x32_bf16 v[70:73], v[166:169], v[224:227], v[70:73]
	v_mfma_f32_16x16x32_bf16 v[66:69], v[174:177], v[224:227], v[66:69]
	s_barrier
	s_add_i32 s36, s45, s79
	v_lshl_add_u64 v[194:195], v[194:195], 0, s[84:85]
	s_mov_b32 m0, s36
	ds_read_b128 v[178:181], v149 offset:49152
	ds_read_b128 v[182:185], v149 offset:50176
	ds_read_b128 v[186:189], v149 offset:51200
	ds_read_b128 v[190:193], v149 offset:52224
	ds_read_b128 v[202:205], v149 offset:53248
	ds_read_b128 v[206:209], v149 offset:54272
	ds_read_b128 v[220:223], v149 offset:55296
	ds_read_b128 v[224:227], v149 offset:56320
	global_load_lds_dwordx4 v[194:195], off
	v_lshl_add_u64 v[194:195], v[198:199], 0, s[84:85]
	s_add_i32 m0, s36, 0x2000
	s_add_i32 s36, s62, s79
	global_load_lds_dwordx4 v[194:195], off
	v_lshl_add_u64 v[194:195], v[200:201], 0, s[84:85]
	s_mov_b32 m0, s36
	s_nop 0
	global_load_lds_dwordx4 v[194:195], off
	v_lshl_add_u64 v[194:195], v[210:211], 0, s[84:85]
	s_add_i32 m0, s36, 0x2000
	s_nop 0
	global_load_lds_dwordx4 v[194:195], off
	v_lshl_add_u64 v[194:195], v[212:213], 0, s[84:85]
	s_mov_b32 m0, s46
	s_nop 0
	global_load_lds_dwordx4 v[194:195], off
	v_lshl_add_u64 v[194:195], v[214:215], 0, s[84:85]
	s_mov_b32 m0, s47
	s_nop 0
	global_load_lds_dwordx4 v[194:195], off
	s_waitcnt vmcnt(8)
	s_waitcnt lgkmcnt(0)
	s_barrier
	s_waitcnt lgkmcnt(0)
	v_mfma_f32_16x16x32_bf16 v[62:65], v[144:147], v[178:181], v[62:65]
	v_mfma_f32_16x16x32_bf16 v[58:61], v[154:157], v[178:181], v[58:61]
	v_mfma_f32_16x16x32_bf16 v[46:49], v[144:147], v[186:189], v[46:49]
	v_mfma_f32_16x16x32_bf16 v[42:45], v[154:157], v[186:189], v[42:45]
	v_mfma_f32_16x16x32_bf16 v[30:33], v[144:147], v[202:205], v[30:33]
	v_mfma_f32_16x16x32_bf16 v[26:29], v[154:157], v[202:205], v[26:29]
	v_mfma_f32_16x16x32_bf16 v[14:17], v[144:147], v[220:223], v[14:17]
	v_mfma_f32_16x16x32_bf16 v[10:13], v[154:157], v[220:223], v[10:13]
	v_mfma_f32_16x16x32_bf16 v[62:65], v[150:153], v[182:185], v[62:65]
	v_mfma_f32_16x16x32_bf16 v[58:61], v[158:161], v[182:185], v[58:61]
	v_mfma_f32_16x16x32_bf16 v[46:49], v[150:153], v[190:193], v[46:49]
	v_mfma_f32_16x16x32_bf16 v[42:45], v[158:161], v[190:193], v[42:45]
	v_mfma_f32_16x16x32_bf16 v[30:33], v[150:153], v[206:209], v[30:33]
	v_mfma_f32_16x16x32_bf16 v[26:29], v[158:161], v[206:209], v[26:29]
	v_mfma_f32_16x16x32_bf16 v[14:17], v[150:153], v[224:227], v[14:17]
	v_mfma_f32_16x16x32_bf16 v[10:13], v[158:161], v[224:227], v[10:13]
	v_mfma_f32_16x16x32_bf16 v[54:57], v[162:165], v[178:181], v[54:57]
	v_mfma_f32_16x16x32_bf16 v[50:53], v[170:173], v[178:181], v[50:53]
	v_mfma_f32_16x16x32_bf16 v[38:41], v[162:165], v[186:189], v[38:41]
	v_mfma_f32_16x16x32_bf16 v[34:37], v[170:173], v[186:189], v[34:37]
	v_mfma_f32_16x16x32_bf16 v[22:25], v[162:165], v[202:205], v[22:25]
	v_mfma_f32_16x16x32_bf16 v[18:21], v[170:173], v[202:205], v[18:21]
	v_mfma_f32_16x16x32_bf16 v[6:9], v[162:165], v[220:223], v[6:9]
	v_mfma_f32_16x16x32_bf16 v[2:5], v[170:173], v[220:223], v[2:5]
	v_mfma_f32_16x16x32_bf16 v[54:57], v[166:169], v[182:185], v[54:57]
	v_mfma_f32_16x16x32_bf16 v[50:53], v[174:177], v[182:185], v[50:53]
	v_mfma_f32_16x16x32_bf16 v[38:41], v[166:169], v[190:193], v[38:41]
	v_mfma_f32_16x16x32_bf16 v[34:37], v[174:177], v[190:193], v[34:37]
	v_mfma_f32_16x16x32_bf16 v[22:25], v[166:169], v[206:209], v[22:25]
	v_mfma_f32_16x16x32_bf16 v[18:21], v[174:177], v[206:209], v[18:21]
	v_mfma_f32_16x16x32_bf16 v[6:9], v[166:169], v[224:227], v[6:9]
	v_mfma_f32_16x16x32_bf16 v[2:5], v[174:177], v[224:227], v[2:5]
	s_barrier
	s_add_u32 s8, s8, 0x100
	s_addc_u32 s9, s9, 0
	s_add_u32 s59, s59, 0x100
	s_addc_u32 s60, s60, 0
	s_cmp_ge_u32 s61, s90
	s_mov_b32 s36, s61
	s_cbranch_scc0 .LBB0_352

.LBB0_438:
	s_add_i32 s58, s36, 2
	s_add_u32 s59, s34, 0x80
	s_addc_u32 s37, s35, 0
	s_add_i32 s62, 0, 0x10000
	s_cmp_eq_u32 s50, s36
	s_cselect_b32 s37, s9, s37
	s_cselect_b32 s36, s8, s59
	v_add_u32_e32 v144, s62, v147
	s_cselect_b32 s61, s21, s57
	s_cselect_b32 s60, s20, s56
	s_add_i32 s59, 0, 0x14000
	ds_read_b128 v[136:139], v144
	ds_read_b128 v[140:143], v144 offset:1024
	ds_read_b128 v[150:153], v144 offset:2048
	ds_read_b128 v[154:157], v144 offset:3072
	v_add_u32_e32 v144, s59, v147
	ds_read_b128 v[158:161], v144
	ds_read_b128 v[162:165], v144 offset:1024
	ds_read_b128 v[166:169], v144 offset:2048
	ds_read_b128 v[170:173], v144 offset:3072
	v_lshl_add_u64 v[144:145], s[34:35], 0, v[132:133]
	s_add_i32 m0, s79, 0xc000
	ds_read_b128 v[174:177], v149
	ds_read_b128 v[178:181], v149 offset:1024
	ds_read_b128 v[182:185], v149 offset:2048
	ds_read_b128 v[186:189], v149 offset:3072
	ds_read_b128 v[190:193], v149 offset:4096
	ds_read_b128 v[202:205], v149 offset:5120
	ds_read_b128 v[206:209], v149 offset:6144
	ds_read_b128 v[220:223], v149 offset:7168
	global_load_lds_dwordx4 v[144:145], off
	v_lshl_add_u64 v[144:145], s[34:35], 0, v[134:135]
	s_add_i32 m0, s79, 0xe000
	s_nop 0
	global_load_lds_dwordx4 v[144:145], off
	s_waitcnt vmcnt(8)
	s_waitcnt lgkmcnt(0)
	s_barrier
	s_waitcnt lgkmcnt(0)
	v_mfma_f32_16x16x32_bf16 v[126:129], v[136:139], v[174:177], v[126:129]
	v_mfma_f32_16x16x32_bf16 v[98:101], v[150:153], v[174:177], v[98:101]
	v_mfma_f32_16x16x32_bf16 v[122:125], v[136:139], v[182:185], v[122:125]
	v_mfma_f32_16x16x32_bf16 v[94:97], v[150:153], v[182:185], v[94:97]
	v_mfma_f32_16x16x32_bf16 v[118:121], v[136:139], v[190:193], v[118:121]
	v_mfma_f32_16x16x32_bf16 v[86:89], v[150:153], v[190:193], v[86:89]
	v_mfma_f32_16x16x32_bf16 v[114:117], v[136:139], v[206:209], v[114:117]
	v_mfma_f32_16x16x32_bf16 v[82:85], v[150:153], v[206:209], v[82:85]
	v_mfma_f32_16x16x32_bf16 v[126:129], v[140:143], v[178:181], v[126:129]
	v_mfma_f32_16x16x32_bf16 v[98:101], v[154:157], v[178:181], v[98:101]
	v_mfma_f32_16x16x32_bf16 v[122:125], v[140:143], v[186:189], v[122:125]
	v_mfma_f32_16x16x32_bf16 v[94:97], v[154:157], v[186:189], v[94:97]
	v_mfma_f32_16x16x32_bf16 v[118:121], v[140:143], v[202:205], v[118:121]
	v_mfma_f32_16x16x32_bf16 v[86:89], v[154:157], v[202:205], v[86:89]
	v_mfma_f32_16x16x32_bf16 v[114:117], v[140:143], v[220:223], v[114:117]
	v_mfma_f32_16x16x32_bf16 v[82:85], v[154:157], v[220:223], v[82:85]
	v_mfma_f32_16x16x32_bf16 v[70:73], v[158:161], v[174:177], v[70:73]
	v_mfma_f32_16x16x32_bf16 v[42:45], v[166:169], v[174:177], v[42:45]
	v_mfma_f32_16x16x32_bf16 v[62:65], v[158:161], v[182:185], v[62:65]
	v_mfma_f32_16x16x32_bf16 v[34:37], v[166:169], v[182:185], v[34:37]
	v_mfma_f32_16x16x32_bf16 v[54:57], v[158:161], v[190:193], v[54:57]
	v_mfma_f32_16x16x32_bf16 v[26:29], v[166:169], v[190:193], v[26:29]
	v_mfma_f32_16x16x32_bf16 v[50:53], v[158:161], v[206:209], v[50:53]
	v_mfma_f32_16x16x32_bf16 v[18:21], v[166:169], v[206:209], v[18:21]
	v_mfma_f32_16x16x32_bf16 v[70:73], v[162:165], v[178:181], v[70:73]
	v_mfma_f32_16x16x32_bf16 v[42:45], v[170:173], v[178:181], v[42:45]
	v_mfma_f32_16x16x32_bf16 v[62:65], v[162:165], v[186:189], v[62:65]
	v_mfma_f32_16x16x32_bf16 v[34:37], v[170:173], v[186:189], v[34:37]
	v_mfma_f32_16x16x32_bf16 v[54:57], v[162:165], v[202:205], v[54:57]
	v_mfma_f32_16x16x32_bf16 v[26:29], v[170:173], v[202:205], v[26:29]
	v_mfma_f32_16x16x32_bf16 v[50:53], v[162:165], v[220:223], v[50:53]
	v_mfma_f32_16x16x32_bf16 v[18:21], v[170:173], v[220:223], v[18:21]
	s_barrier
	s_add_i32 s62, s62, s78
	v_lshl_add_u64 v[144:145], s[60:61], 0, v[0:1]
	s_mov_b32 m0, s62
	ds_read_b128 v[174:177], v149 offset:16384
	ds_read_b128 v[178:181], v149 offset:17408
	ds_read_b128 v[182:185], v149 offset:18432
	ds_read_b128 v[186:189], v149 offset:19456
	ds_read_b128 v[190:193], v149 offset:20480
	ds_read_b128 v[202:205], v149 offset:21504
	ds_read_b128 v[206:209], v149 offset:22528
	ds_read_b128 v[220:223], v149 offset:23552
	global_load_lds_dwordx4 v[144:145], off
	s_add_i32 m0, s62, 0x2000
	v_lshl_add_u64 v[194:195], s[60:61], 0, v[130:131]
	s_add_u32 s60, s60, s80
	s_addc_u32 s61, s61, 0
	s_add_i32 s59, s59, s78
	global_load_lds_dwordx4 v[194:195], off
	v_lshl_add_u64 v[198:199], s[60:61], 0, v[0:1]
	s_mov_b32 m0, s59
	v_lshl_add_u64 v[200:201], s[60:61], 0, v[130:131]
	global_load_lds_dwordx4 v[198:199], off
	s_add_i32 m0, s59, 0x2000
	v_lshl_add_u64 v[210:211], s[36:37], 0, v[0:1]
	global_load_lds_dwordx4 v[200:201], off
	s_mov_b32 m0, s79
	v_lshl_add_u64 v[212:213], s[36:37], 0, v[130:131]
	global_load_lds_dwordx4 v[210:211], off
	s_mov_b32 m0, s46
	s_nop 0
	global_load_lds_dwordx4 v[212:213], off
	s_waitcnt vmcnt(8)
	s_waitcnt lgkmcnt(0)
	s_barrier
	s_waitcnt lgkmcnt(0)
	v_mfma_f32_16x16x32_bf16 v[110:113], v[136:139], v[174:177], v[110:113]
	v_mfma_f32_16x16x32_bf16 v[78:81], v[150:153], v[174:177], v[78:81]
	v_mfma_f32_16x16x32_bf16 v[106:109], v[136:139], v[182:185], v[106:109]
	v_mfma_f32_16x16x32_bf16 v[74:77], v[150:153], v[182:185], v[74:77]
	v_mfma_f32_16x16x32_bf16 v[102:105], v[136:139], v[190:193], v[102:105]
	v_mfma_f32_16x16x32_bf16 v[66:69], v[150:153], v[190:193], v[66:69]
	v_mfma_f32_16x16x32_bf16 v[90:93], v[136:139], v[206:209], v[90:93]
	v_mfma_f32_16x16x32_bf16 v[58:61], v[150:153], v[206:209], v[58:61]
	v_mfma_f32_16x16x32_bf16 v[110:113], v[140:143], v[178:181], v[110:113]
	v_mfma_f32_16x16x32_bf16 v[78:81], v[154:157], v[178:181], v[78:81]
	v_mfma_f32_16x16x32_bf16 v[106:109], v[140:143], v[186:189], v[106:109]
	v_mfma_f32_16x16x32_bf16 v[74:77], v[154:157], v[186:189], v[74:77]
	v_mfma_f32_16x16x32_bf16 v[102:105], v[140:143], v[202:205], v[102:105]
	v_mfma_f32_16x16x32_bf16 v[66:69], v[154:157], v[202:205], v[66:69]
	v_mfma_f32_16x16x32_bf16 v[90:93], v[140:143], v[220:223], v[90:93]
	v_mfma_f32_16x16x32_bf16 v[58:61], v[154:157], v[220:223], v[58:61]
	v_mfma_f32_16x16x32_bf16 v[46:49], v[158:161], v[174:177], v[46:49]
	v_mfma_f32_16x16x32_bf16 v[14:17], v[166:169], v[174:177], v[14:17]
	v_mfma_f32_16x16x32_bf16 v[38:41], v[158:161], v[182:185], v[38:41]
	v_mfma_f32_16x16x32_bf16 v[10:13], v[166:169], v[182:185], v[10:13]
	v_mfma_f32_16x16x32_bf16 v[30:33], v[158:161], v[190:193], v[30:33]
	v_mfma_f32_16x16x32_bf16 v[6:9], v[166:169], v[190:193], v[6:9]
	v_mfma_f32_16x16x32_bf16 v[22:25], v[158:161], v[206:209], v[22:25]
	v_mfma_f32_16x16x32_bf16 v[2:5], v[166:169], v[206:209], v[2:5]
	v_mfma_f32_16x16x32_bf16 v[46:49], v[162:165], v[178:181], v[46:49]
	v_mfma_f32_16x16x32_bf16 v[14:17], v[170:173], v[178:181], v[14:17]
	v_mfma_f32_16x16x32_bf16 v[38:41], v[162:165], v[186:189], v[38:41]
	v_mfma_f32_16x16x32_bf16 v[10:13], v[170:173], v[186:189], v[10:13]
	v_mfma_f32_16x16x32_bf16 v[30:33], v[162:165], v[202:205], v[30:33]
	v_mfma_f32_16x16x32_bf16 v[6:9], v[170:173], v[202:205], v[6:9]
	v_mfma_f32_16x16x32_bf16 v[22:25], v[162:165], v[220:223], v[22:25]
	v_mfma_f32_16x16x32_bf16 v[2:5], v[170:173], v[220:223], v[2:5]
	s_barrier
	s_add_i32 s59, 0, 0x18000
	s_add_i32 s60, 0, 0x1c000
	v_add_u32_e32 v154, s59, v147
	v_add_u32_e32 v170, s60, v147
	ds_read_b128 v[136:139], v154
	ds_read_b128 v[140:143], v154 offset:1024
	ds_read_b128 v[150:153], v154 offset:2048
	ds_read_b128 v[154:157], v154 offset:3072
	ds_read_b128 v[158:161], v170
	ds_read_b128 v[162:165], v170 offset:1024
	ds_read_b128 v[166:169], v170 offset:2048
	ds_read_b128 v[170:173], v170 offset:3072
	s_add_u32 s36, s36, s80
	s_addc_u32 s37, s37, 0
	s_mov_b32 m0, s47
	v_lshl_add_u64 v[214:215], s[36:37], 0, v[0:1]
	ds_read_b128 v[174:177], v149 offset:32768
	ds_read_b128 v[178:181], v149 offset:33792
	ds_read_b128 v[182:185], v149 offset:34816
	ds_read_b128 v[186:189], v149 offset:35840
	ds_read_b128 v[190:193], v149 offset:36864
	ds_read_b128 v[202:205], v149 offset:37888
	ds_read_b128 v[206:209], v149 offset:38912
	ds_read_b128 v[220:223], v149 offset:39936
	global_load_lds_dwordx4 v[214:215], off
	v_lshl_add_u64 v[214:215], s[36:37], 0, v[130:131]
	s_mov_b32 m0, s82
	s_nop 0
	global_load_lds_dwordx4 v[214:215], off
	s_waitcnt vmcnt(8)
	s_waitcnt lgkmcnt(0)
	s_barrier
	s_waitcnt lgkmcnt(0)
	v_mfma_f32_16x16x32_bf16 v[126:129], v[136:139], v[174:177], v[126:129]
	v_mfma_f32_16x16x32_bf16 v[98:101], v[150:153], v[174:177], v[98:101]
	v_mfma_f32_16x16x32_bf16 v[122:125], v[136:139], v[182:185], v[122:125]
	v_mfma_f32_16x16x32_bf16 v[94:97], v[150:153], v[182:185], v[94:97]
	v_mfma_f32_16x16x32_bf16 v[118:121], v[136:139], v[190:193], v[118:121]
	v_mfma_f32_16x16x32_bf16 v[86:89], v[150:153], v[190:193], v[86:89]
	v_mfma_f32_16x16x32_bf16 v[114:117], v[136:139], v[206:209], v[114:117]
	v_mfma_f32_16x16x32_bf16 v[82:85], v[150:153], v[206:209], v[82:85]
	v_mfma_f32_16x16x32_bf16 v[126:129], v[140:143], v[178:181], v[126:129]
	v_mfma_f32_16x16x32_bf16 v[98:101], v[154:157], v[178:181], v[98:101]
	v_mfma_f32_16x16x32_bf16 v[122:125], v[140:143], v[186:189], v[122:125]
	v_mfma_f32_16x16x32_bf16 v[94:97], v[154:157], v[186:189], v[94:97]
	v_mfma_f32_16x16x32_bf16 v[118:121], v[140:143], v[202:205], v[118:121]
	v_mfma_f32_16x16x32_bf16 v[86:89], v[154:157], v[202:205], v[86:89]
	v_mfma_f32_16x16x32_bf16 v[114:117], v[140:143], v[220:223], v[114:117]
	v_mfma_f32_16x16x32_bf16 v[82:85], v[154:157], v[220:223], v[82:85]
	v_mfma_f32_16x16x32_bf16 v[70:73], v[158:161], v[174:177], v[70:73]
	v_mfma_f32_16x16x32_bf16 v[42:45], v[166:169], v[174:177], v[42:45]
	v_mfma_f32_16x16x32_bf16 v[62:65], v[158:161], v[182:185], v[62:65]
	v_mfma_f32_16x16x32_bf16 v[34:37], v[166:169], v[182:185], v[34:37]
	v_mfma_f32_16x16x32_bf16 v[54:57], v[158:161], v[190:193], v[54:57]
	v_mfma_f32_16x16x32_bf16 v[26:29], v[166:169], v[190:193], v[26:29]
	v_mfma_f32_16x16x32_bf16 v[50:53], v[158:161], v[206:209], v[50:53]
	v_mfma_f32_16x16x32_bf16 v[18:21], v[166:169], v[206:209], v[18:21]
	v_mfma_f32_16x16x32_bf16 v[70:73], v[162:165], v[178:181], v[70:73]
	v_mfma_f32_16x16x32_bf16 v[42:45], v[170:173], v[178:181], v[42:45]
	v_mfma_f32_16x16x32_bf16 v[62:65], v[162:165], v[186:189], v[62:65]
	v_mfma_f32_16x16x32_bf16 v[34:37], v[170:173], v[186:189], v[34:37]
	v_mfma_f32_16x16x32_bf16 v[54:57], v[162:165], v[202:205], v[54:57]
	v_mfma_f32_16x16x32_bf16 v[26:29], v[170:173], v[202:205], v[26:29]
	v_mfma_f32_16x16x32_bf16 v[50:53], v[162:165], v[220:223], v[50:53]
	v_mfma_f32_16x16x32_bf16 v[18:21], v[170:173], v[220:223], v[18:21]
	s_barrier
	s_add_i32 s36, s59, s78
	v_lshl_add_u64 v[144:145], v[144:145], 0, s[84:85]
	s_mov_b32 m0, s36
	ds_read_b128 v[174:177], v149 offset:49152
	ds_read_b128 v[178:181], v149 offset:50176
	ds_read_b128 v[182:185], v149 offset:51200
	ds_read_b128 v[186:189], v149 offset:52224
	ds_read_b128 v[190:193], v149 offset:53248
	ds_read_b128 v[202:205], v149 offset:54272
	ds_read_b128 v[206:209], v149 offset:55296
	ds_read_b128 v[220:223], v149 offset:56320
	global_load_lds_dwordx4 v[144:145], off
	v_lshl_add_u64 v[144:145], v[194:195], 0, s[84:85]
	s_add_i32 m0, s36, 0x2000
	s_add_i32 s36, s60, s78
	global_load_lds_dwordx4 v[144:145], off
	v_lshl_add_u64 v[144:145], v[198:199], 0, s[84:85]
	s_mov_b32 m0, s36
	s_nop 0
	global_load_lds_dwordx4 v[144:145], off
	v_lshl_add_u64 v[144:145], v[200:201], 0, s[84:85]
	s_add_i32 m0, s36, 0x2000
	s_nop 0
	global_load_lds_dwordx4 v[144:145], off
	v_lshl_add_u64 v[144:145], v[210:211], 0, s[84:85]
	s_mov_b32 m0, s48
	s_nop 0
	global_load_lds_dwordx4 v[144:145], off
	v_lshl_add_u64 v[144:145], v[212:213], 0, s[84:85]
	s_mov_b32 m0, s49
	s_nop 0
	global_load_lds_dwordx4 v[144:145], off
	s_waitcnt vmcnt(8)
	s_waitcnt lgkmcnt(0)
	s_barrier
	s_waitcnt lgkmcnt(0)
	v_mfma_f32_16x16x32_bf16 v[110:113], v[136:139], v[174:177], v[110:113]
	v_mfma_f32_16x16x32_bf16 v[78:81], v[150:153], v[174:177], v[78:81]
	v_mfma_f32_16x16x32_bf16 v[106:109], v[136:139], v[182:185], v[106:109]
	v_mfma_f32_16x16x32_bf16 v[74:77], v[150:153], v[182:185], v[74:77]
	v_mfma_f32_16x16x32_bf16 v[102:105], v[136:139], v[190:193], v[102:105]
	v_mfma_f32_16x16x32_bf16 v[66:69], v[150:153], v[190:193], v[66:69]
	v_mfma_f32_16x16x32_bf16 v[90:93], v[136:139], v[206:209], v[90:93]
	v_mfma_f32_16x16x32_bf16 v[58:61], v[150:153], v[206:209], v[58:61]
	v_mfma_f32_16x16x32_bf16 v[110:113], v[140:143], v[178:181], v[110:113]
	v_mfma_f32_16x16x32_bf16 v[78:81], v[154:157], v[178:181], v[78:81]
	v_mfma_f32_16x16x32_bf16 v[106:109], v[140:143], v[186:189], v[106:109]
	v_mfma_f32_16x16x32_bf16 v[74:77], v[154:157], v[186:189], v[74:77]
	v_mfma_f32_16x16x32_bf16 v[102:105], v[140:143], v[202:205], v[102:105]
	v_mfma_f32_16x16x32_bf16 v[66:69], v[154:157], v[202:205], v[66:69]
	v_mfma_f32_16x16x32_bf16 v[90:93], v[140:143], v[220:223], v[90:93]
	v_mfma_f32_16x16x32_bf16 v[58:61], v[154:157], v[220:223], v[58:61]
	v_mfma_f32_16x16x32_bf16 v[46:49], v[158:161], v[174:177], v[46:49]
	v_mfma_f32_16x16x32_bf16 v[14:17], v[166:169], v[174:177], v[14:17]
	v_mfma_f32_16x16x32_bf16 v[38:41], v[158:161], v[182:185], v[38:41]
	v_mfma_f32_16x16x32_bf16 v[10:13], v[166:169], v[182:185], v[10:13]
	v_mfma_f32_16x16x32_bf16 v[30:33], v[158:161], v[190:193], v[30:33]
	v_mfma_f32_16x16x32_bf16 v[6:9], v[166:169], v[190:193], v[6:9]
	v_mfma_f32_16x16x32_bf16 v[22:25], v[158:161], v[206:209], v[22:25]
	v_mfma_f32_16x16x32_bf16 v[2:5], v[166:169], v[206:209], v[2:5]
	v_mfma_f32_16x16x32_bf16 v[46:49], v[162:165], v[178:181], v[46:49]
	v_mfma_f32_16x16x32_bf16 v[14:17], v[170:173], v[178:181], v[14:17]
	v_mfma_f32_16x16x32_bf16 v[38:41], v[162:165], v[186:189], v[38:41]
	v_mfma_f32_16x16x32_bf16 v[10:13], v[170:173], v[186:189], v[10:13]
	v_mfma_f32_16x16x32_bf16 v[30:33], v[162:165], v[202:205], v[30:33]
	v_mfma_f32_16x16x32_bf16 v[6:9], v[170:173], v[202:205], v[6:9]
	v_mfma_f32_16x16x32_bf16 v[22:25], v[162:165], v[220:223], v[22:25]
	v_mfma_f32_16x16x32_bf16 v[2:5], v[170:173], v[220:223], v[2:5]
	s_barrier
	s_add_u32 s34, s34, 0x100
	s_addc_u32 s35, s35, 0
	s_add_u32 s56, s56, 0x100
	s_addc_u32 s57, s57, 0
	s_cmp_ge_u32 s58, s87
	s_mov_b32 s36, s58
	s_cbranch_scc0 .LBB0_438
	s_and_b64 vcc, exec, s[10:11]
	s_cbranch_vccz .LBB0_441
	s_barrier

.LBB0_483:
	s_add_i32 s61, s38, 2
	s_add_u32 s62, s20, s36
	s_addc_u32 s39, s21, s37
	s_add_u32 s64, s4, s36
	s_addc_u32 s63, s5, s37
	s_add_i32 s65, 0, 0x10000
	s_cmp_eq_u32 s56, s38
	s_cselect_b32 s39, s11, s39
	s_cselect_b32 s38, s10, s62
	v_add_u32_e32 v147, s65, v145
	s_cselect_b32 s63, s35, s63
	s_cselect_b32 s62, s34, s64
	s_add_i32 s64, 0, 0x14000
	ds_read_b128 v[148:151], v147
	ds_read_b128 v[152:155], v147 offset:1024
	ds_read_b128 v[156:159], v147 offset:2048
	ds_read_b128 v[160:163], v147 offset:3072
	v_add_u32_e32 v147, s64, v145
	ds_read_b128 v[164:167], v147
	ds_read_b128 v[168:171], v147 offset:1024
	ds_read_b128 v[172:175], v147 offset:2048
	ds_read_b128 v[176:179], v147 offset:3072
	v_lshl_add_u64 v[194:195], s[20:21], 0, v[142:143]
	s_add_i32 m0, s48, 0xc000
	ds_read_b128 v[180:183], v146
	ds_read_b128 v[184:187], v146 offset:1024
	ds_read_b128 v[190:193], v146 offset:2048
	ds_read_b128 v[202:205], v146 offset:3072
	ds_read_b128 v[206:209], v146 offset:4096
	ds_read_b128 v[220:223], v146 offset:5120
	ds_read_b128 v[224:227], v146 offset:6144
	ds_read_b128 v[228:231], v146 offset:7168
	global_load_lds_dwordx4 v[194:195], off
	v_lshl_add_u64 v[194:195], s[20:21], 0, v[140:141]
	s_add_i32 m0, s48, 0xe000
	s_nop 0
	global_load_lds_dwordx4 v[194:195], off
	s_waitcnt vmcnt(8)
	s_waitcnt lgkmcnt(0)
	s_barrier
	s_waitcnt lgkmcnt(0)
	v_mfma_f32_16x16x32_bf16 v[126:129], v[148:151], v[180:183], v[126:129]
	v_mfma_f32_16x16x32_bf16 v[122:125], v[156:159], v[180:183], v[122:125]
	v_mfma_f32_16x16x32_bf16 v[118:121], v[148:151], v[190:193], v[118:121]
	v_mfma_f32_16x16x32_bf16 v[114:117], v[156:159], v[190:193], v[114:117]
	v_mfma_f32_16x16x32_bf16 v[110:113], v[148:151], v[206:209], v[110:113]
	v_mfma_f32_16x16x32_bf16 v[106:109], v[156:159], v[206:209], v[106:109]
	v_mfma_f32_16x16x32_bf16 v[102:105], v[148:151], v[224:227], v[102:105]
	v_mfma_f32_16x16x32_bf16 v[98:101], v[156:159], v[224:227], v[98:101]
	v_mfma_f32_16x16x32_bf16 v[126:129], v[152:155], v[184:187], v[126:129]
	v_mfma_f32_16x16x32_bf16 v[122:125], v[160:163], v[184:187], v[122:125]
	v_mfma_f32_16x16x32_bf16 v[118:121], v[152:155], v[202:205], v[118:121]
	v_mfma_f32_16x16x32_bf16 v[114:117], v[160:163], v[202:205], v[114:117]
	v_mfma_f32_16x16x32_bf16 v[110:113], v[152:155], v[220:223], v[110:113]
	v_mfma_f32_16x16x32_bf16 v[106:109], v[160:163], v[220:223], v[106:109]
	v_mfma_f32_16x16x32_bf16 v[102:105], v[152:155], v[228:231], v[102:105]
	v_mfma_f32_16x16x32_bf16 v[98:101], v[160:163], v[228:231], v[98:101]
	v_mfma_f32_16x16x32_bf16 v[62:65], v[164:167], v[180:183], v[62:65]
	v_mfma_f32_16x16x32_bf16 v[58:61], v[172:175], v[180:183], v[58:61]
	v_mfma_f32_16x16x32_bf16 v[54:57], v[164:167], v[190:193], v[54:57]
	v_mfma_f32_16x16x32_bf16 v[50:53], v[172:175], v[190:193], v[50:53]
	v_mfma_f32_16x16x32_bf16 v[46:49], v[164:167], v[206:209], v[46:49]
	v_mfma_f32_16x16x32_bf16 v[42:45], v[172:175], v[206:209], v[42:45]
	v_mfma_f32_16x16x32_bf16 v[38:41], v[164:167], v[224:227], v[38:41]
	v_mfma_f32_16x16x32_bf16 v[34:37], v[172:175], v[224:227], v[34:37]
	v_mfma_f32_16x16x32_bf16 v[62:65], v[168:171], v[184:187], v[62:65]
	v_mfma_f32_16x16x32_bf16 v[58:61], v[176:179], v[184:187], v[58:61]
	v_mfma_f32_16x16x32_bf16 v[54:57], v[168:171], v[202:205], v[54:57]
	v_mfma_f32_16x16x32_bf16 v[50:53], v[176:179], v[202:205], v[50:53]
	v_mfma_f32_16x16x32_bf16 v[46:49], v[168:171], v[220:223], v[46:49]
	v_mfma_f32_16x16x32_bf16 v[42:45], v[176:179], v[220:223], v[42:45]
	v_mfma_f32_16x16x32_bf16 v[38:41], v[168:171], v[228:231], v[38:41]
	v_mfma_f32_16x16x32_bf16 v[34:37], v[176:179], v[228:231], v[34:37]
	s_barrier
	s_add_i32 s65, s65, s47
	v_lshl_add_u64 v[194:195], s[62:63], 0, v[0:1]
	s_mov_b32 m0, s65
	ds_read_b128 v[180:183], v146 offset:16384
	ds_read_b128 v[184:187], v146 offset:17408
	ds_read_b128 v[190:193], v146 offset:18432
	ds_read_b128 v[202:205], v146 offset:19456
	ds_read_b128 v[206:209], v146 offset:20480
	ds_read_b128 v[220:223], v146 offset:21504
	ds_read_b128 v[224:227], v146 offset:22528
	ds_read_b128 v[228:231], v146 offset:23552
	global_load_lds_dwordx4 v[194:195], off
	s_add_i32 m0, s65, 0x2000
	v_lshl_add_u64 v[198:199], s[62:63], 0, v[134:135]
	s_add_u32 s62, s62, s80
	s_addc_u32 s63, s63, 0
	s_add_i32 s64, s64, s47
	global_load_lds_dwordx4 v[198:199], off
	v_lshl_add_u64 v[200:201], s[62:63], 0, v[0:1]
	s_mov_b32 m0, s64
	v_lshl_add_u64 v[210:211], s[62:63], 0, v[134:135]
	global_load_lds_dwordx4 v[200:201], off
	s_add_i32 m0, s64, 0x2000
	v_lshl_add_u64 v[212:213], s[38:39], 0, v[130:131]
	global_load_lds_dwordx4 v[210:211], off
	s_mov_b32 m0, s48
	v_lshl_add_u64 v[214:215], s[38:39], 0, v[132:133]
	global_load_lds_dwordx4 v[212:213], off
	s_mov_b32 m0, s50
	s_nop 0
	global_load_lds_dwordx4 v[214:215], off
	s_waitcnt vmcnt(8)
	s_waitcnt lgkmcnt(0)
	s_barrier
	s_waitcnt lgkmcnt(0)
	v_mfma_f32_16x16x32_bf16 v[94:97], v[148:151], v[180:183], v[94:97]
	v_mfma_f32_16x16x32_bf16 v[90:93], v[156:159], v[180:183], v[90:93]
	v_mfma_f32_16x16x32_bf16 v[86:89], v[148:151], v[190:193], v[86:89]
	v_mfma_f32_16x16x32_bf16 v[82:85], v[156:159], v[190:193], v[82:85]
	v_mfma_f32_16x16x32_bf16 v[78:81], v[148:151], v[206:209], v[78:81]
	v_mfma_f32_16x16x32_bf16 v[74:77], v[156:159], v[206:209], v[74:77]
	v_mfma_f32_16x16x32_bf16 v[70:73], v[148:151], v[224:227], v[70:73]
	v_mfma_f32_16x16x32_bf16 v[66:69], v[156:159], v[224:227], v[66:69]
	v_mfma_f32_16x16x32_bf16 v[94:97], v[152:155], v[184:187], v[94:97]
	v_mfma_f32_16x16x32_bf16 v[90:93], v[160:163], v[184:187], v[90:93]
	v_mfma_f32_16x16x32_bf16 v[86:89], v[152:155], v[202:205], v[86:89]
	v_mfma_f32_16x16x32_bf16 v[82:85], v[160:163], v[202:205], v[82:85]
	v_mfma_f32_16x16x32_bf16 v[78:81], v[152:155], v[220:223], v[78:81]
	v_mfma_f32_16x16x32_bf16 v[74:77], v[160:163], v[220:223], v[74:77]
	v_mfma_f32_16x16x32_bf16 v[70:73], v[152:155], v[228:231], v[70:73]
	v_mfma_f32_16x16x32_bf16 v[66:69], v[160:163], v[228:231], v[66:69]
	v_mfma_f32_16x16x32_bf16 v[30:33], v[164:167], v[180:183], v[30:33]
	v_mfma_f32_16x16x32_bf16 v[26:29], v[172:175], v[180:183], v[26:29]
	v_mfma_f32_16x16x32_bf16 v[22:25], v[164:167], v[190:193], v[22:25]
	v_mfma_f32_16x16x32_bf16 v[18:21], v[172:175], v[190:193], v[18:21]
	v_mfma_f32_16x16x32_bf16 v[14:17], v[164:167], v[206:209], v[14:17]
	v_mfma_f32_16x16x32_bf16 v[10:13], v[172:175], v[206:209], v[10:13]
	v_mfma_f32_16x16x32_bf16 v[6:9], v[164:167], v[224:227], v[6:9]
	v_mfma_f32_16x16x32_bf16 v[2:5], v[172:175], v[224:227], v[2:5]
	v_mfma_f32_16x16x32_bf16 v[30:33], v[168:171], v[184:187], v[30:33]
	v_mfma_f32_16x16x32_bf16 v[26:29], v[176:179], v[184:187], v[26:29]
	v_mfma_f32_16x16x32_bf16 v[22:25], v[168:171], v[202:205], v[22:25]
	v_mfma_f32_16x16x32_bf16 v[18:21], v[176:179], v[202:205], v[18:21]
	v_mfma_f32_16x16x32_bf16 v[14:17], v[168:171], v[220:223], v[14:17]
	v_mfma_f32_16x16x32_bf16 v[10:13], v[176:179], v[220:223], v[10:13]
	v_mfma_f32_16x16x32_bf16 v[6:9], v[168:171], v[228:231], v[6:9]
	v_mfma_f32_16x16x32_bf16 v[2:5], v[176:179], v[228:231], v[2:5]
	s_barrier
	s_add_i32 s62, 0, 0x18000
	v_add_u32_e32 v147, s62, v145
	s_add_i32 s63, 0, 0x1c000
	ds_read_b128 v[148:151], v147
	ds_read_b128 v[152:155], v147 offset:1024
	ds_read_b128 v[156:159], v147 offset:2048
	ds_read_b128 v[160:163], v147 offset:3072
	v_add_u32_e32 v147, s63, v145
	ds_read_b128 v[164:167], v147
	ds_read_b128 v[168:171], v147 offset:1024
	ds_read_b128 v[172:175], v147 offset:2048
	ds_read_b128 v[176:179], v147 offset:3072
	s_add_u32 s38, s38, s80
	s_addc_u32 s39, s39, 0
	s_mov_b32 m0, s51
	v_lshl_add_u64 v[216:217], s[38:39], 0, v[130:131]
	ds_read_b128 v[180:183], v146 offset:32768
	ds_read_b128 v[184:187], v146 offset:33792
	ds_read_b128 v[190:193], v146 offset:34816
	ds_read_b128 v[202:205], v146 offset:35840
	ds_read_b128 v[206:209], v146 offset:36864
	ds_read_b128 v[220:223], v146 offset:37888
	ds_read_b128 v[224:227], v146 offset:38912
	ds_read_b128 v[228:231], v146 offset:39936
	global_load_lds_dwordx4 v[216:217], off
	v_lshl_add_u64 v[216:217], s[38:39], 0, v[132:133]
	s_mov_b32 m0, s52
	s_nop 0
	global_load_lds_dwordx4 v[216:217], off
	s_waitcnt vmcnt(8)
	s_waitcnt lgkmcnt(0)
	s_barrier
	s_waitcnt lgkmcnt(0)
	v_mfma_f32_16x16x32_bf16 v[126:129], v[148:151], v[180:183], v[126:129]
	v_mfma_f32_16x16x32_bf16 v[122:125], v[156:159], v[180:183], v[122:125]
	v_mfma_f32_16x16x32_bf16 v[118:121], v[148:151], v[190:193], v[118:121]
	v_mfma_f32_16x16x32_bf16 v[114:117], v[156:159], v[190:193], v[114:117]
	v_mfma_f32_16x16x32_bf16 v[110:113], v[148:151], v[206:209], v[110:113]
	v_mfma_f32_16x16x32_bf16 v[106:109], v[156:159], v[206:209], v[106:109]
	v_mfma_f32_16x16x32_bf16 v[102:105], v[148:151], v[224:227], v[102:105]
	v_mfma_f32_16x16x32_bf16 v[98:101], v[156:159], v[224:227], v[98:101]
	v_mfma_f32_16x16x32_bf16 v[126:129], v[152:155], v[184:187], v[126:129]
	v_mfma_f32_16x16x32_bf16 v[122:125], v[160:163], v[184:187], v[122:125]
	v_mfma_f32_16x16x32_bf16 v[118:121], v[152:155], v[202:205], v[118:121]
	v_mfma_f32_16x16x32_bf16 v[114:117], v[160:163], v[202:205], v[114:117]
	v_mfma_f32_16x16x32_bf16 v[110:113], v[152:155], v[220:223], v[110:113]
	v_mfma_f32_16x16x32_bf16 v[106:109], v[160:163], v[220:223], v[106:109]
	v_mfma_f32_16x16x32_bf16 v[102:105], v[152:155], v[228:231], v[102:105]
	v_mfma_f32_16x16x32_bf16 v[98:101], v[160:163], v[228:231], v[98:101]
	v_mfma_f32_16x16x32_bf16 v[62:65], v[164:167], v[180:183], v[62:65]
	v_mfma_f32_16x16x32_bf16 v[58:61], v[172:175], v[180:183], v[58:61]
	v_mfma_f32_16x16x32_bf16 v[54:57], v[164:167], v[190:193], v[54:57]
	v_mfma_f32_16x16x32_bf16 v[50:53], v[172:175], v[190:193], v[50:53]
	v_mfma_f32_16x16x32_bf16 v[46:49], v[164:167], v[206:209], v[46:49]
	v_mfma_f32_16x16x32_bf16 v[42:45], v[172:175], v[206:209], v[42:45]
	v_mfma_f32_16x16x32_bf16 v[38:41], v[164:167], v[224:227], v[38:41]
	v_mfma_f32_16x16x32_bf16 v[34:37], v[172:175], v[224:227], v[34:37]
	v_mfma_f32_16x16x32_bf16 v[62:65], v[168:171], v[184:187], v[62:65]
	v_mfma_f32_16x16x32_bf16 v[58:61], v[176:179], v[184:187], v[58:61]
	v_mfma_f32_16x16x32_bf16 v[54:57], v[168:171], v[202:205], v[54:57]
	v_mfma_f32_16x16x32_bf16 v[50:53], v[176:179], v[202:205], v[50:53]
	v_mfma_f32_16x16x32_bf16 v[46:49], v[168:171], v[220:223], v[46:49]
	v_mfma_f32_16x16x32_bf16 v[42:45], v[176:179], v[220:223], v[42:45]
	v_mfma_f32_16x16x32_bf16 v[38:41], v[168:171], v[228:231], v[38:41]
	v_mfma_f32_16x16x32_bf16 v[34:37], v[176:179], v[228:231], v[34:37]
	s_barrier
	s_add_i32 s38, s62, s47
	v_lshl_add_u64 v[194:195], v[194:195], 0, s[84:85]
	s_mov_b32 m0, s38
	ds_read_b128 v[180:183], v146 offset:49152
	ds_read_b128 v[184:187], v146 offset:50176
	ds_read_b128 v[190:193], v146 offset:51200
	ds_read_b128 v[202:205], v146 offset:52224
	ds_read_b128 v[206:209], v146 offset:53248
	ds_read_b128 v[220:223], v146 offset:54272
	ds_read_b128 v[224:227], v146 offset:55296
	ds_read_b128 v[228:231], v146 offset:56320
	global_load_lds_dwordx4 v[194:195], off
	v_lshl_add_u64 v[194:195], v[198:199], 0, s[84:85]
	s_add_i32 m0, s38, 0x2000
	s_add_i32 s38, s63, s47
	global_load_lds_dwordx4 v[194:195], off
	v_lshl_add_u64 v[194:195], v[200:201], 0, s[84:85]
	s_mov_b32 m0, s38
	s_nop 0
	global_load_lds_dwordx4 v[194:195], off
	v_lshl_add_u64 v[194:195], v[210:211], 0, s[84:85]
	s_add_i32 m0, s38, 0x2000
	s_nop 0
	global_load_lds_dwordx4 v[194:195], off
	v_lshl_add_u64 v[194:195], v[212:213], 0, s[84:85]
	s_mov_b32 m0, s54
	s_nop 0
	global_load_lds_dwordx4 v[194:195], off
	v_lshl_add_u64 v[194:195], v[214:215], 0, s[84:85]
	s_mov_b32 m0, s55
	s_nop 0
	global_load_lds_dwordx4 v[194:195], off
	s_waitcnt vmcnt(8)
	s_waitcnt lgkmcnt(0)
	s_barrier
	s_waitcnt lgkmcnt(0)
	v_mfma_f32_16x16x32_bf16 v[94:97], v[148:151], v[180:183], v[94:97]
	v_mfma_f32_16x16x32_bf16 v[90:93], v[156:159], v[180:183], v[90:93]
	v_mfma_f32_16x16x32_bf16 v[86:89], v[148:151], v[190:193], v[86:89]
	v_mfma_f32_16x16x32_bf16 v[82:85], v[156:159], v[190:193], v[82:85]
	v_mfma_f32_16x16x32_bf16 v[78:81], v[148:151], v[206:209], v[78:81]
	v_mfma_f32_16x16x32_bf16 v[74:77], v[156:159], v[206:209], v[74:77]
	v_mfma_f32_16x16x32_bf16 v[70:73], v[148:151], v[224:227], v[70:73]
	v_mfma_f32_16x16x32_bf16 v[66:69], v[156:159], v[224:227], v[66:69]
	v_mfma_f32_16x16x32_bf16 v[94:97], v[152:155], v[184:187], v[94:97]
	v_mfma_f32_16x16x32_bf16 v[90:93], v[160:163], v[184:187], v[90:93]
	v_mfma_f32_16x16x32_bf16 v[86:89], v[152:155], v[202:205], v[86:89]
	v_mfma_f32_16x16x32_bf16 v[82:85], v[160:163], v[202:205], v[82:85]
	v_mfma_f32_16x16x32_bf16 v[78:81], v[152:155], v[220:223], v[78:81]
	v_mfma_f32_16x16x32_bf16 v[74:77], v[160:163], v[220:223], v[74:77]
	v_mfma_f32_16x16x32_bf16 v[70:73], v[152:155], v[228:231], v[70:73]
	v_mfma_f32_16x16x32_bf16 v[66:69], v[160:163], v[228:231], v[66:69]
	v_mfma_f32_16x16x32_bf16 v[30:33], v[164:167], v[180:183], v[30:33]
	v_mfma_f32_16x16x32_bf16 v[26:29], v[172:175], v[180:183], v[26:29]
	v_mfma_f32_16x16x32_bf16 v[22:25], v[164:167], v[190:193], v[22:25]
	v_mfma_f32_16x16x32_bf16 v[18:21], v[172:175], v[190:193], v[18:21]
	v_mfma_f32_16x16x32_bf16 v[14:17], v[164:167], v[206:209], v[14:17]
	v_mfma_f32_16x16x32_bf16 v[10:13], v[172:175], v[206:209], v[10:13]
	v_mfma_f32_16x16x32_bf16 v[6:9], v[164:167], v[224:227], v[6:9]
	v_mfma_f32_16x16x32_bf16 v[2:5], v[172:175], v[224:227], v[2:5]
	v_mfma_f32_16x16x32_bf16 v[30:33], v[168:171], v[184:187], v[30:33]
	v_mfma_f32_16x16x32_bf16 v[26:29], v[176:179], v[184:187], v[26:29]
	v_mfma_f32_16x16x32_bf16 v[22:25], v[168:171], v[202:205], v[22:25]
	v_mfma_f32_16x16x32_bf16 v[18:21], v[176:179], v[202:205], v[18:21]
	v_mfma_f32_16x16x32_bf16 v[14:17], v[168:171], v[220:223], v[14:17]
	v_mfma_f32_16x16x32_bf16 v[10:13], v[176:179], v[220:223], v[10:13]
	v_mfma_f32_16x16x32_bf16 v[6:9], v[168:171], v[228:231], v[6:9]
	v_mfma_f32_16x16x32_bf16 v[2:5], v[176:179], v[228:231], v[2:5]
	s_barrier
	s_add_u32 s36, s36, 0x100
	s_addc_u32 s37, s37, 0
	v_lshl_add_u64 v[142:143], v[142:143], 0, s[88:89]
	v_lshl_add_u64 v[140:141], v[140:141], 0, s[88:89]
	s_cmp_ge_u32 s61, s53
	s_mov_b32 s38, s61
	s_cbranch_scc0 .LBB0_483
	s_and_b64 vcc, exec, s[8:9]
	s_cbranch_vccnz .LBB0_471
	v_mov_b32_e32 v2, 0
	s_mov_b32 s2, s58
	s_mov_b32 s78, s59
	s_mov_b64 s[4:5], s[34:35]
	s_mov_b64 s[20:21], s[10:11]
	s_mov_b32 s57, s60
	v_mov_b32_e32 v3, v2
	v_mov_b32_e32 v4, v2
	v_mov_b32_e32 v5, v2
	v_mov_b32_e32 v6, v2
	v_mov_b32_e32 v7, v2
	v_mov_b32_e32 v8, v2
	v_mov_b32_e32 v9, v2
	v_mov_b32_e32 v10, v2
	v_mov_b32_e32 v11, v2
	v_mov_b32_e32 v12, v2
	v_mov_b32_e32 v13, v2
	v_mov_b32_e32 v14, v2
	v_mov_b32_e32 v15, v2
	v_mov_b32_e32 v16, v2
	v_mov_b32_e32 v17, v2
	v_mov_b32_e32 v18, v2
	v_mov_b32_e32 v19, v2
	v_mov_b32_e32 v20, v2
	v_mov_b32_e32 v21, v2
	v_mov_b32_e32 v22, v2
	v_mov_b32_e32 v23, v2
	v_mov_b32_e32 v24, v2
	v_mov_b32_e32 v25, v2
	v_mov_b32_e32 v26, v2
	v_mov_b32_e32 v27, v2
	v_mov_b32_e32 v28, v2
	v_mov_b32_e32 v29, v2
	v_mov_b32_e32 v30, v2
	v_mov_b32_e32 v31, v2
	v_mov_b32_e32 v32, v2
	v_mov_b32_e32 v33, v2
	v_mov_b32_e32 v66, v2
	v_mov_b32_e32 v67, v2
	v_mov_b32_e32 v68, v2
	v_mov_b32_e32 v69, v2
	v_mov_b32_e32 v70, v2
	v_mov_b32_e32 v71, v2
	v_mov_b32_e32 v72, v2
	v_mov_b32_e32 v73, v2
	v_mov_b32_e32 v74, v2
	v_mov_b32_e32 v75, v2
	v_mov_b32_e32 v76, v2
	v_mov_b32_e32 v77, v2
	v_mov_b32_e32 v78, v2
	v_mov_b32_e32 v79, v2
	v_mov_b32_e32 v80, v2
	v_mov_b32_e32 v81, v2
	v_mov_b32_e32 v82, v2
	v_mov_b32_e32 v83, v2
	v_mov_b32_e32 v84, v2
	v_mov_b32_e32 v85, v2
	v_mov_b32_e32 v86, v2
	v_mov_b32_e32 v87, v2
	v_mov_b32_e32 v88, v2
	v_mov_b32_e32 v89, v2
	v_mov_b32_e32 v90, v2
	v_mov_b32_e32 v91, v2
	v_mov_b32_e32 v92, v2
	v_mov_b32_e32 v93, v2
	v_mov_b32_e32 v94, v2
	v_mov_b32_e32 v95, v2
	v_mov_b32_e32 v96, v2
	v_mov_b32_e32 v97, v2
	v_mov_b32_e32 v34, v2
	v_mov_b32_e32 v35, v2
	v_mov_b32_e32 v36, v2
	v_mov_b32_e32 v37, v2
	v_mov_b32_e32 v38, v2
	v_mov_b32_e32 v39, v2
	v_mov_b32_e32 v40, v2
	v_mov_b32_e32 v41, v2
	v_mov_b32_e32 v42, v2
	v_mov_b32_e32 v43, v2
	v_mov_b32_e32 v44, v2
	v_mov_b32_e32 v45, v2
	v_mov_b32_e32 v46, v2
	v_mov_b32_e32 v47, v2
	v_mov_b32_e32 v48, v2
	v_mov_b32_e32 v49, v2
	v_mov_b32_e32 v50, v2
	v_mov_b32_e32 v51, v2
	v_mov_b32_e32 v52, v2
	v_mov_b32_e32 v53, v2
	v_mov_b32_e32 v54, v2
	v_mov_b32_e32 v55, v2
	v_mov_b32_e32 v56, v2
	v_mov_b32_e32 v57, v2
	v_mov_b32_e32 v58, v2
	v_mov_b32_e32 v59, v2
	v_mov_b32_e32 v60, v2
	v_mov_b32_e32 v61, v2
	v_mov_b32_e32 v62, v2
	v_mov_b32_e32 v63, v2
	v_mov_b32_e32 v64, v2
	v_mov_b32_e32 v65, v2
	v_mov_b32_e32 v98, v2
	v_mov_b32_e32 v99, v2
	v_mov_b32_e32 v100, v2
	v_mov_b32_e32 v101, v2
	v_mov_b32_e32 v102, v2
	v_mov_b32_e32 v103, v2
	v_mov_b32_e32 v104, v2
	v_mov_b32_e32 v105, v2
	v_mov_b32_e32 v106, v2
	v_mov_b32_e32 v107, v2
	v_mov_b32_e32 v108, v2
	v_mov_b32_e32 v109, v2
	v_mov_b32_e32 v110, v2
	v_mov_b32_e32 v111, v2
	v_mov_b32_e32 v112, v2
	v_mov_b32_e32 v113, v2
	v_mov_b32_e32 v114, v2
	v_mov_b32_e32 v115, v2
	v_mov_b32_e32 v116, v2
	v_mov_b32_e32 v117, v2
	v_mov_b32_e32 v118, v2
	v_mov_b32_e32 v119, v2
	v_mov_b32_e32 v120, v2
	v_mov_b32_e32 v121, v2
	v_mov_b32_e32 v122, v2
	v_mov_b32_e32 v123, v2
	v_mov_b32_e32 v124, v2
	v_mov_b32_e32 v125, v2
	v_mov_b32_e32 v126, v2
	v_mov_b32_e32 v127, v2
	v_mov_b32_e32 v128, v2
	v_mov_b32_e32 v129, v2
	s_branch .LBB0_471

.LBB0_691:
	s_ashr_i32 s15, s14, 31
	s_lshl_b64 s[16:17], s[14:15], 19
	s_add_u32 s16, s82, s16
	s_addc_u32 s17, s83, s17
	s_and_b64 s[18:19], s[6:7], exec
	s_cselect_b32 s15, s17, s5
	s_cselect_b32 s46, s16, s4
	s_ashr_i32 s11, s10, 31
	s_lshl_b64 s[18:19], s[10:11], 19
	s_add_u32 s18, s34, s18
	s_addc_u32 s19, s35, s19
	s_and_b64 s[28:29], s[6:7], exec
	s_cselect_b32 s11, s19, s21
	s_cselect_b32 s47, s18, s20
	s_add_u32 s4, s4, 0x40080
	s_addc_u32 s5, s5, 0
	s_add_u32 s48, s20, 0x100
	s_addc_u32 s49, s21, 0
	s_mov_b32 s50, -2
	s_add_u32 s20, s4, 0xfffc0080
	s_addc_u32 s21, s5, -1
	s_add_i32 s51, 0, 0x10000
	s_cmp_eq_u32 s50, 12
	s_cselect_b32 s29, s15, s21
	s_cselect_b32 s28, s46, s20
	v_add_u32_e32 v140, s51, v143
	s_cselect_b32 s21, s11, s49
	s_cselect_b32 s20, s47, s48
	s_add_i32 s54, 0, 0x14000
	ds_read_b128 v[146:149], v140
	ds_read_b128 v[150:153], v140 offset:1024
	ds_read_b128 v[154:157], v140 offset:2048
	ds_read_b128 v[158:161], v140 offset:3072
	v_add_u32_e32 v140, s54, v143
	ds_read_b128 v[162:165], v140
	ds_read_b128 v[166:169], v140 offset:1024
	ds_read_b128 v[170:173], v140 offset:2048
	ds_read_b128 v[174:177], v140 offset:3072
	v_lshl_add_u64 v[140:141], s[4:5], 0, v[136:137]
	s_add_i32 m0, s38, 0xc000
	ds_read_b128 v[178:181], v145
	ds_read_b128 v[182:185], v145 offset:1024
	ds_read_b128 v[186:189], v145 offset:2048
	ds_read_b128 v[190:193], v145 offset:3072
	ds_read_b128 v[202:205], v145 offset:4096
	ds_read_b128 v[206:209], v145 offset:5120
	ds_read_b128 v[220:223], v145 offset:6144
	ds_read_b128 v[224:227], v145 offset:7168
	global_load_lds_dwordx4 v[140:141], off
	v_lshl_add_u64 v[140:141], s[4:5], 0, v[138:139]
	s_add_i32 m0, s38, 0xe000
	s_nop 0
	global_load_lds_dwordx4 v[140:141], off
	s_waitcnt vmcnt(8)
	s_waitcnt lgkmcnt(0)
	s_barrier
	s_waitcnt lgkmcnt(0)
	v_mfma_f32_16x16x32_bf16 v[126:129], v[146:149], v[178:181], 0
	v_mfma_f32_16x16x32_bf16 v[118:121], v[154:157], v[178:181], 0
	v_mfma_f32_16x16x32_bf16 v[110:113], v[146:149], v[186:189], 0
	v_mfma_f32_16x16x32_bf16 v[102:105], v[154:157], v[186:189], 0
	v_mfma_f32_16x16x32_bf16 v[94:97], v[146:149], v[202:205], 0
	v_mfma_f32_16x16x32_bf16 v[86:89], v[154:157], v[202:205], 0
	v_mfma_f32_16x16x32_bf16 v[78:81], v[146:149], v[220:223], 0
	v_mfma_f32_16x16x32_bf16 v[70:73], v[154:157], v[220:223], 0
	v_mfma_f32_16x16x32_bf16 v[126:129], v[150:153], v[182:185], v[126:129]
	v_mfma_f32_16x16x32_bf16 v[118:121], v[158:161], v[182:185], v[118:121]
	v_mfma_f32_16x16x32_bf16 v[110:113], v[150:153], v[190:193], v[110:113]
	v_mfma_f32_16x16x32_bf16 v[102:105], v[158:161], v[190:193], v[102:105]
	v_mfma_f32_16x16x32_bf16 v[94:97], v[150:153], v[206:209], v[94:97]
	v_mfma_f32_16x16x32_bf16 v[86:89], v[158:161], v[206:209], v[86:89]
	v_mfma_f32_16x16x32_bf16 v[78:81], v[150:153], v[224:227], v[78:81]
	v_mfma_f32_16x16x32_bf16 v[70:73], v[158:161], v[224:227], v[70:73]
	v_mfma_f32_16x16x32_bf16 v[122:125], v[162:165], v[178:181], 0
	v_mfma_f32_16x16x32_bf16 v[114:117], v[170:173], v[178:181], 0
	v_mfma_f32_16x16x32_bf16 v[106:109], v[162:165], v[186:189], 0
	v_mfma_f32_16x16x32_bf16 v[98:101], v[170:173], v[186:189], 0
	v_mfma_f32_16x16x32_bf16 v[90:93], v[162:165], v[202:205], 0
	v_mfma_f32_16x16x32_bf16 v[82:85], v[170:173], v[202:205], 0
	v_mfma_f32_16x16x32_bf16 v[74:77], v[162:165], v[220:223], 0
	v_mfma_f32_16x16x32_bf16 v[66:69], v[170:173], v[220:223], 0
	v_mfma_f32_16x16x32_bf16 v[122:125], v[166:169], v[182:185], v[122:125]
	v_mfma_f32_16x16x32_bf16 v[114:117], v[174:177], v[182:185], v[114:117]
	v_mfma_f32_16x16x32_bf16 v[106:109], v[166:169], v[190:193], v[106:109]
	v_mfma_f32_16x16x32_bf16 v[98:101], v[174:177], v[190:193], v[98:101]
	v_mfma_f32_16x16x32_bf16 v[90:93], v[166:169], v[206:209], v[90:93]
	v_mfma_f32_16x16x32_bf16 v[82:85], v[174:177], v[206:209], v[82:85]
	v_mfma_f32_16x16x32_bf16 v[74:77], v[166:169], v[224:227], v[74:77]
	v_mfma_f32_16x16x32_bf16 v[66:69], v[174:177], v[224:227], v[66:69]
	s_barrier
	s_add_i32 s51, s51, s36
	v_lshl_add_u64 v[140:141], s[20:21], 0, v[0:1]
	s_mov_b32 m0, s51
	ds_read_b128 v[178:181], v145 offset:16384
	ds_read_b128 v[182:185], v145 offset:17408
	ds_read_b128 v[186:189], v145 offset:18432
	ds_read_b128 v[190:193], v145 offset:19456
	ds_read_b128 v[202:205], v145 offset:20480
	ds_read_b128 v[206:209], v145 offset:21504
	ds_read_b128 v[220:223], v145 offset:22528
	ds_read_b128 v[224:227], v145 offset:23552
	global_load_lds_dwordx4 v[140:141], off
	s_add_i32 m0, s51, 0x2000
	s_add_u32 s52, s20, 0x40000
	v_lshl_add_u64 v[194:195], s[20:21], 0, v[130:131]
	s_addc_u32 s53, s21, 0
	s_add_i32 s51, s54, s36
	global_load_lds_dwordx4 v[194:195], off
	v_lshl_add_u64 v[198:199], s[52:53], 0, v[0:1]
	s_mov_b32 m0, s51
	v_lshl_add_u64 v[200:201], s[28:29], 0, v[132:133]
	global_load_lds_dwordx4 v[198:199], off
	v_lshl_add_u64 v[198:199], s[52:53], 0, v[130:131]
	s_add_i32 m0, s51, 0x2000
	s_nop 0
	global_load_lds_dwordx4 v[198:199], off
	v_lshl_add_u64 v[198:199], s[28:29], 0, v[134:135]
	s_mov_b32 m0, s38
	s_nop 0
	global_load_lds_dwordx4 v[198:199], off
	s_mov_b32 m0, s39
	s_nop 0
	global_load_lds_dwordx4 v[200:201], off
	s_waitcnt vmcnt(8)
	s_waitcnt lgkmcnt(0)
	s_barrier
	s_waitcnt lgkmcnt(0)
	v_mfma_f32_16x16x32_bf16 v[62:65], v[146:149], v[178:181], 0
	v_mfma_f32_16x16x32_bf16 v[54:57], v[154:157], v[178:181], 0
	v_mfma_f32_16x16x32_bf16 v[46:49], v[146:149], v[186:189], 0
	v_mfma_f32_16x16x32_bf16 v[38:41], v[154:157], v[186:189], 0
	v_mfma_f32_16x16x32_bf16 v[30:33], v[146:149], v[202:205], 0
	v_mfma_f32_16x16x32_bf16 v[22:25], v[154:157], v[202:205], 0
	v_mfma_f32_16x16x32_bf16 v[14:17], v[146:149], v[220:223], 0
	v_mfma_f32_16x16x32_bf16 v[6:9], v[154:157], v[220:223], 0
	v_mfma_f32_16x16x32_bf16 v[62:65], v[150:153], v[182:185], v[62:65]
	v_mfma_f32_16x16x32_bf16 v[54:57], v[158:161], v[182:185], v[54:57]
	v_mfma_f32_16x16x32_bf16 v[46:49], v[150:153], v[190:193], v[46:49]
	v_mfma_f32_16x16x32_bf16 v[38:41], v[158:161], v[190:193], v[38:41]
	v_mfma_f32_16x16x32_bf16 v[30:33], v[150:153], v[206:209], v[30:33]
	v_mfma_f32_16x16x32_bf16 v[22:25], v[158:161], v[206:209], v[22:25]
	v_mfma_f32_16x16x32_bf16 v[14:17], v[150:153], v[224:227], v[14:17]
	v_mfma_f32_16x16x32_bf16 v[6:9], v[158:161], v[224:227], v[6:9]
	v_mfma_f32_16x16x32_bf16 v[58:61], v[162:165], v[178:181], 0
	v_mfma_f32_16x16x32_bf16 v[50:53], v[170:173], v[178:181], 0
	v_mfma_f32_16x16x32_bf16 v[42:45], v[162:165], v[186:189], 0
	v_mfma_f32_16x16x32_bf16 v[34:37], v[170:173], v[186:189], 0
	v_mfma_f32_16x16x32_bf16 v[26:29], v[162:165], v[202:205], 0
	v_mfma_f32_16x16x32_bf16 v[18:21], v[170:173], v[202:205], 0
	v_mfma_f32_16x16x32_bf16 v[10:13], v[162:165], v[220:223], 0
	v_mfma_f32_16x16x32_bf16 v[2:5], v[170:173], v[220:223], 0
	v_mfma_f32_16x16x32_bf16 v[58:61], v[166:169], v[182:185], v[58:61]
	v_mfma_f32_16x16x32_bf16 v[50:53], v[174:177], v[182:185], v[50:53]
	v_mfma_f32_16x16x32_bf16 v[42:45], v[166:169], v[190:193], v[42:45]
	v_mfma_f32_16x16x32_bf16 v[34:37], v[174:177], v[190:193], v[34:37]
	v_mfma_f32_16x16x32_bf16 v[26:29], v[166:169], v[206:209], v[26:29]
	v_mfma_f32_16x16x32_bf16 v[18:21], v[174:177], v[206:209], v[18:21]
	v_mfma_f32_16x16x32_bf16 v[10:13], v[166:169], v[224:227], v[10:13]
	v_mfma_f32_16x16x32_bf16 v[2:5], v[174:177], v[224:227], v[2:5]
	s_barrier
	s_add_i32 s51, 0, 0x18000
	s_add_i32 s52, 0, 0x1c000
	v_add_u32_e32 v158, s51, v143
	v_add_u32_e32 v174, s52, v143
	ds_read_b128 v[146:149], v158
	ds_read_b128 v[150:153], v158 offset:1024
	ds_read_b128 v[154:157], v158 offset:2048
	ds_read_b128 v[158:161], v158 offset:3072
	ds_read_b128 v[162:165], v174
	ds_read_b128 v[166:169], v174 offset:1024
	ds_read_b128 v[170:173], v174 offset:2048
	ds_read_b128 v[174:177], v174 offset:3072
	s_add_u32 s28, s28, 0x40000
	s_addc_u32 s29, s29, 0
	s_mov_b32 m0, s40
	v_lshl_add_u64 v[210:211], s[28:29], 0, v[134:135]
	ds_read_b128 v[178:181], v145 offset:32768
	ds_read_b128 v[182:185], v145 offset:33792
	ds_read_b128 v[186:189], v145 offset:34816
	ds_read_b128 v[190:193], v145 offset:35840
	ds_read_b128 v[202:205], v145 offset:36864
	ds_read_b128 v[206:209], v145 offset:37888
	ds_read_b128 v[220:223], v145 offset:38912
	ds_read_b128 v[224:227], v145 offset:39936
	global_load_lds_dwordx4 v[210:211], off
	v_lshl_add_u64 v[210:211], s[28:29], 0, v[132:133]
	s_mov_b32 m0, s41
	s_nop 0
	global_load_lds_dwordx4 v[210:211], off
	s_waitcnt vmcnt(8)
	s_waitcnt lgkmcnt(0)
	s_barrier
	s_waitcnt lgkmcnt(0)
	v_mfma_f32_16x16x32_bf16 v[126:129], v[146:149], v[178:181], v[126:129]
	v_mfma_f32_16x16x32_bf16 v[118:121], v[154:157], v[178:181], v[118:121]
	v_mfma_f32_16x16x32_bf16 v[110:113], v[146:149], v[186:189], v[110:113]
	v_mfma_f32_16x16x32_bf16 v[102:105], v[154:157], v[186:189], v[102:105]
	v_mfma_f32_16x16x32_bf16 v[94:97], v[146:149], v[202:205], v[94:97]
	v_mfma_f32_16x16x32_bf16 v[86:89], v[154:157], v[202:205], v[86:89]
	v_mfma_f32_16x16x32_bf16 v[78:81], v[146:149], v[220:223], v[78:81]
	v_mfma_f32_16x16x32_bf16 v[70:73], v[154:157], v[220:223], v[70:73]
	v_mfma_f32_16x16x32_bf16 v[126:129], v[150:153], v[182:185], v[126:129]
	v_mfma_f32_16x16x32_bf16 v[118:121], v[158:161], v[182:185], v[118:121]
	v_mfma_f32_16x16x32_bf16 v[110:113], v[150:153], v[190:193], v[110:113]
	v_mfma_f32_16x16x32_bf16 v[102:105], v[158:161], v[190:193], v[102:105]
	v_mfma_f32_16x16x32_bf16 v[94:97], v[150:153], v[206:209], v[94:97]
	v_mfma_f32_16x16x32_bf16 v[86:89], v[158:161], v[206:209], v[86:89]
	v_mfma_f32_16x16x32_bf16 v[78:81], v[150:153], v[224:227], v[78:81]
	v_mfma_f32_16x16x32_bf16 v[70:73], v[158:161], v[224:227], v[70:73]
	v_mfma_f32_16x16x32_bf16 v[122:125], v[162:165], v[178:181], v[122:125]
	v_mfma_f32_16x16x32_bf16 v[114:117], v[170:173], v[178:181], v[114:117]
	v_mfma_f32_16x16x32_bf16 v[106:109], v[162:165], v[186:189], v[106:109]
	v_mfma_f32_16x16x32_bf16 v[98:101], v[170:173], v[186:189], v[98:101]
	v_mfma_f32_16x16x32_bf16 v[90:93], v[162:165], v[202:205], v[90:93]
	v_mfma_f32_16x16x32_bf16 v[82:85], v[170:173], v[202:205], v[82:85]
	v_mfma_f32_16x16x32_bf16 v[74:77], v[162:165], v[220:223], v[74:77]
	v_mfma_f32_16x16x32_bf16 v[66:69], v[170:173], v[220:223], v[66:69]
	v_mfma_f32_16x16x32_bf16 v[122:125], v[166:169], v[182:185], v[122:125]
	v_mfma_f32_16x16x32_bf16 v[114:117], v[174:177], v[182:185], v[114:117]
	v_mfma_f32_16x16x32_bf16 v[106:109], v[166:169], v[190:193], v[106:109]
	v_mfma_f32_16x16x32_bf16 v[98:101], v[174:177], v[190:193], v[98:101]
	v_mfma_f32_16x16x32_bf16 v[90:93], v[166:169], v[206:209], v[90:93]
	v_mfma_f32_16x16x32_bf16 v[82:85], v[174:177], v[206:209], v[82:85]
	v_mfma_f32_16x16x32_bf16 v[74:77], v[166:169], v[224:227], v[74:77]
	v_mfma_f32_16x16x32_bf16 v[66:69], v[174:177], v[224:227], v[66:69]
	s_barrier
	s_add_i32 s28, s51, s36
	v_lshl_add_u64 v[140:141], v[140:141], 0, s[84:85]
	s_mov_b32 m0, s28
	ds_read_b128 v[178:181], v145 offset:49152
	ds_read_b128 v[182:185], v145 offset:50176
	ds_read_b128 v[186:189], v145 offset:51200
	ds_read_b128 v[190:193], v145 offset:52224
	ds_read_b128 v[202:205], v145 offset:53248
	ds_read_b128 v[206:209], v145 offset:54272
	ds_read_b128 v[220:223], v145 offset:55296
	ds_read_b128 v[224:227], v145 offset:56320
	global_load_lds_dwordx4 v[140:141], off
	s_add_i32 m0, s28, 0x2000
	s_add_u32 s20, s20, 0x40080
	v_lshl_add_u64 v[140:141], v[194:195], 0, s[84:85]
	s_addc_u32 s21, s21, 0
	s_add_i32 s28, s52, s36
	global_load_lds_dwordx4 v[140:141], off
	v_lshl_add_u64 v[140:141], s[20:21], 0, v[0:1]
	s_mov_b32 m0, s28
	s_nop 0
	global_load_lds_dwordx4 v[140:141], off
	v_lshl_add_u64 v[140:141], s[20:21], 0, v[130:131]
	s_add_i32 m0, s28, 0x2000
	s_nop 0
	global_load_lds_dwordx4 v[140:141], off
	v_lshl_add_u64 v[140:141], v[198:199], 0, s[84:85]
	s_mov_b32 m0, s76
	s_nop 0
	global_load_lds_dwordx4 v[140:141], off
	v_lshl_add_u64 v[140:141], v[200:201], 0, s[84:85]
	s_mov_b32 m0, s77
	s_nop 0
	global_load_lds_dwordx4 v[140:141], off
	s_waitcnt vmcnt(8)
	s_waitcnt lgkmcnt(0)
	s_barrier
	s_waitcnt lgkmcnt(0)
	v_mfma_f32_16x16x32_bf16 v[62:65], v[146:149], v[178:181], v[62:65]
	v_mfma_f32_16x16x32_bf16 v[54:57], v[154:157], v[178:181], v[54:57]
	v_mfma_f32_16x16x32_bf16 v[46:49], v[146:149], v[186:189], v[46:49]
	v_mfma_f32_16x16x32_bf16 v[38:41], v[154:157], v[186:189], v[38:41]
	v_mfma_f32_16x16x32_bf16 v[30:33], v[146:149], v[202:205], v[30:33]
	v_mfma_f32_16x16x32_bf16 v[22:25], v[154:157], v[202:205], v[22:25]
	v_mfma_f32_16x16x32_bf16 v[14:17], v[146:149], v[220:223], v[14:17]
	v_mfma_f32_16x16x32_bf16 v[6:9], v[154:157], v[220:223], v[6:9]
	v_mfma_f32_16x16x32_bf16 v[62:65], v[150:153], v[182:185], v[62:65]
	v_mfma_f32_16x16x32_bf16 v[54:57], v[158:161], v[182:185], v[54:57]
	v_mfma_f32_16x16x32_bf16 v[46:49], v[150:153], v[190:193], v[46:49]
	v_mfma_f32_16x16x32_bf16 v[38:41], v[158:161], v[190:193], v[38:41]
	v_mfma_f32_16x16x32_bf16 v[30:33], v[150:153], v[206:209], v[30:33]
	v_mfma_f32_16x16x32_bf16 v[22:25], v[158:161], v[206:209], v[22:25]
	v_mfma_f32_16x16x32_bf16 v[14:17], v[150:153], v[224:227], v[14:17]
	v_mfma_f32_16x16x32_bf16 v[6:9], v[158:161], v[224:227], v[6:9]
	v_mfma_f32_16x16x32_bf16 v[58:61], v[162:165], v[178:181], v[58:61]
	v_mfma_f32_16x16x32_bf16 v[50:53], v[170:173], v[178:181], v[50:53]
	v_mfma_f32_16x16x32_bf16 v[42:45], v[162:165], v[186:189], v[42:45]
	v_mfma_f32_16x16x32_bf16 v[34:37], v[170:173], v[186:189], v[34:37]
	v_mfma_f32_16x16x32_bf16 v[26:29], v[162:165], v[202:205], v[26:29]
	v_mfma_f32_16x16x32_bf16 v[18:21], v[170:173], v[202:205], v[18:21]
	v_mfma_f32_16x16x32_bf16 v[10:13], v[162:165], v[220:223], v[10:13]
	v_mfma_f32_16x16x32_bf16 v[2:5], v[170:173], v[220:223], v[2:5]
	v_mfma_f32_16x16x32_bf16 v[58:61], v[166:169], v[182:185], v[58:61]
	v_mfma_f32_16x16x32_bf16 v[50:53], v[174:177], v[182:185], v[50:53]
	v_mfma_f32_16x16x32_bf16 v[42:45], v[166:169], v[190:193], v[42:45]
	v_mfma_f32_16x16x32_bf16 v[34:37], v[174:177], v[190:193], v[34:37]
	v_mfma_f32_16x16x32_bf16 v[26:29], v[166:169], v[206:209], v[26:29]
	v_mfma_f32_16x16x32_bf16 v[18:21], v[174:177], v[206:209], v[18:21]
	v_mfma_f32_16x16x32_bf16 v[10:13], v[166:169], v[224:227], v[10:13]
	v_mfma_f32_16x16x32_bf16 v[2:5], v[174:177], v[224:227], v[2:5]
	s_barrier
	s_add_i32 s50, s50, 2
	s_add_u32 s4, s4, 0x100
	s_addc_u32 s5, s5, 0
	s_add_u32 s48, s48, 0x100
	s_addc_u32 s49, s49, 0
	s_cmp_gt_u32 s50, 13
	s_cbranch_scc1 .Lpeel_exit_swi
.LBB0_692:
	s_add_u32 s20, s4, 0xfffc0080
	s_addc_u32 s21, s5, -1
	s_add_i32 s51, 0, 0x10000
	s_cmp_eq_u32 s50, 12
	s_cselect_b32 s29, s15, s21
	s_cselect_b32 s28, s46, s20
	v_add_u32_e32 v140, s51, v143
	s_cselect_b32 s21, s11, s49
	s_cselect_b32 s20, s47, s48
	s_add_i32 s54, 0, 0x14000
	ds_read_b128 v[146:149], v140
	ds_read_b128 v[150:153], v140 offset:1024
	ds_read_b128 v[154:157], v140 offset:2048
	ds_read_b128 v[158:161], v140 offset:3072
	v_add_u32_e32 v140, s54, v143
	ds_read_b128 v[162:165], v140
	ds_read_b128 v[166:169], v140 offset:1024
	ds_read_b128 v[170:173], v140 offset:2048
	ds_read_b128 v[174:177], v140 offset:3072
	v_lshl_add_u64 v[140:141], s[4:5], 0, v[136:137]
	s_add_i32 m0, s38, 0xc000
	ds_read_b128 v[178:181], v145
	ds_read_b128 v[182:185], v145 offset:1024
	ds_read_b128 v[186:189], v145 offset:2048
	ds_read_b128 v[190:193], v145 offset:3072
	ds_read_b128 v[202:205], v145 offset:4096
	ds_read_b128 v[206:209], v145 offset:5120
	ds_read_b128 v[220:223], v145 offset:6144
	ds_read_b128 v[224:227], v145 offset:7168
	global_load_lds_dwordx4 v[140:141], off
	v_lshl_add_u64 v[140:141], s[4:5], 0, v[138:139]
	s_add_i32 m0, s38, 0xe000
	s_nop 0
	global_load_lds_dwordx4 v[140:141], off
	s_waitcnt vmcnt(8)
	s_waitcnt lgkmcnt(0)
	s_barrier
	s_waitcnt lgkmcnt(0)
	v_mfma_f32_16x16x32_bf16 v[126:129], v[146:149], v[178:181], v[126:129]
	v_mfma_f32_16x16x32_bf16 v[118:121], v[154:157], v[178:181], v[118:121]
	v_mfma_f32_16x16x32_bf16 v[110:113], v[146:149], v[186:189], v[110:113]
	v_mfma_f32_16x16x32_bf16 v[102:105], v[154:157], v[186:189], v[102:105]
	v_mfma_f32_16x16x32_bf16 v[94:97], v[146:149], v[202:205], v[94:97]
	v_mfma_f32_16x16x32_bf16 v[86:89], v[154:157], v[202:205], v[86:89]
	v_mfma_f32_16x16x32_bf16 v[78:81], v[146:149], v[220:223], v[78:81]
	v_mfma_f32_16x16x32_bf16 v[70:73], v[154:157], v[220:223], v[70:73]
	v_mfma_f32_16x16x32_bf16 v[126:129], v[150:153], v[182:185], v[126:129]
	v_mfma_f32_16x16x32_bf16 v[118:121], v[158:161], v[182:185], v[118:121]
	v_mfma_f32_16x16x32_bf16 v[110:113], v[150:153], v[190:193], v[110:113]
	v_mfma_f32_16x16x32_bf16 v[102:105], v[158:161], v[190:193], v[102:105]
	v_mfma_f32_16x16x32_bf16 v[94:97], v[150:153], v[206:209], v[94:97]
	v_mfma_f32_16x16x32_bf16 v[86:89], v[158:161], v[206:209], v[86:89]
	v_mfma_f32_16x16x32_bf16 v[78:81], v[150:153], v[224:227], v[78:81]
	v_mfma_f32_16x16x32_bf16 v[70:73], v[158:161], v[224:227], v[70:73]
	v_mfma_f32_16x16x32_bf16 v[122:125], v[162:165], v[178:181], v[122:125]
	v_mfma_f32_16x16x32_bf16 v[114:117], v[170:173], v[178:181], v[114:117]
	v_mfma_f32_16x16x32_bf16 v[106:109], v[162:165], v[186:189], v[106:109]
	v_mfma_f32_16x16x32_bf16 v[98:101], v[170:173], v[186:189], v[98:101]
	v_mfma_f32_16x16x32_bf16 v[90:93], v[162:165], v[202:205], v[90:93]
	v_mfma_f32_16x16x32_bf16 v[82:85], v[170:173], v[202:205], v[82:85]
	v_mfma_f32_16x16x32_bf16 v[74:77], v[162:165], v[220:223], v[74:77]
	v_mfma_f32_16x16x32_bf16 v[66:69], v[170:173], v[220:223], v[66:69]
	v_mfma_f32_16x16x32_bf16 v[122:125], v[166:169], v[182:185], v[122:125]
	v_mfma_f32_16x16x32_bf16 v[114:117], v[174:177], v[182:185], v[114:117]
	v_mfma_f32_16x16x32_bf16 v[106:109], v[166:169], v[190:193], v[106:109]
	v_mfma_f32_16x16x32_bf16 v[98:101], v[174:177], v[190:193], v[98:101]
	v_mfma_f32_16x16x32_bf16 v[90:93], v[166:169], v[206:209], v[90:93]
	v_mfma_f32_16x16x32_bf16 v[82:85], v[174:177], v[206:209], v[82:85]
	v_mfma_f32_16x16x32_bf16 v[74:77], v[166:169], v[224:227], v[74:77]
	v_mfma_f32_16x16x32_bf16 v[66:69], v[174:177], v[224:227], v[66:69]
	s_barrier
	s_add_i32 s51, s51, s36
	v_lshl_add_u64 v[140:141], s[20:21], 0, v[0:1]
	s_mov_b32 m0, s51
	ds_read_b128 v[178:181], v145 offset:16384
	ds_read_b128 v[182:185], v145 offset:17408
	ds_read_b128 v[186:189], v145 offset:18432
	ds_read_b128 v[190:193], v145 offset:19456
	ds_read_b128 v[202:205], v145 offset:20480
	ds_read_b128 v[206:209], v145 offset:21504
	ds_read_b128 v[220:223], v145 offset:22528
	ds_read_b128 v[224:227], v145 offset:23552
	global_load_lds_dwordx4 v[140:141], off
	s_add_i32 m0, s51, 0x2000
	s_add_u32 s52, s20, 0x40000
	v_lshl_add_u64 v[194:195], s[20:21], 0, v[130:131]
	s_addc_u32 s53, s21, 0
	s_add_i32 s51, s54, s36
	global_load_lds_dwordx4 v[194:195], off
	v_lshl_add_u64 v[198:199], s[52:53], 0, v[0:1]
	s_mov_b32 m0, s51
	v_lshl_add_u64 v[200:201], s[28:29], 0, v[132:133]
	global_load_lds_dwordx4 v[198:199], off
	v_lshl_add_u64 v[198:199], s[52:53], 0, v[130:131]
	s_add_i32 m0, s51, 0x2000
	s_nop 0
	global_load_lds_dwordx4 v[198:199], off
	v_lshl_add_u64 v[198:199], s[28:29], 0, v[134:135]
	s_mov_b32 m0, s38
	s_nop 0
	global_load_lds_dwordx4 v[198:199], off
	s_mov_b32 m0, s39
	s_nop 0
	global_load_lds_dwordx4 v[200:201], off
	s_waitcnt vmcnt(8)
	s_waitcnt lgkmcnt(0)
	s_barrier
	s_waitcnt lgkmcnt(0)
	v_mfma_f32_16x16x32_bf16 v[62:65], v[146:149], v[178:181], v[62:65]
	v_mfma_f32_16x16x32_bf16 v[54:57], v[154:157], v[178:181], v[54:57]
	v_mfma_f32_16x16x32_bf16 v[46:49], v[146:149], v[186:189], v[46:49]
	v_mfma_f32_16x16x32_bf16 v[38:41], v[154:157], v[186:189], v[38:41]
	v_mfma_f32_16x16x32_bf16 v[30:33], v[146:149], v[202:205], v[30:33]
	v_mfma_f32_16x16x32_bf16 v[22:25], v[154:157], v[202:205], v[22:25]
	v_mfma_f32_16x16x32_bf16 v[14:17], v[146:149], v[220:223], v[14:17]
	v_mfma_f32_16x16x32_bf16 v[6:9], v[154:157], v[220:223], v[6:9]
	v_mfma_f32_16x16x32_bf16 v[62:65], v[150:153], v[182:185], v[62:65]
	v_mfma_f32_16x16x32_bf16 v[54:57], v[158:161], v[182:185], v[54:57]
	v_mfma_f32_16x16x32_bf16 v[46:49], v[150:153], v[190:193], v[46:49]
	v_mfma_f32_16x16x32_bf16 v[38:41], v[158:161], v[190:193], v[38:41]
	v_mfma_f32_16x16x32_bf16 v[30:33], v[150:153], v[206:209], v[30:33]
	v_mfma_f32_16x16x32_bf16 v[22:25], v[158:161], v[206:209], v[22:25]
	v_mfma_f32_16x16x32_bf16 v[14:17], v[150:153], v[224:227], v[14:17]
	v_mfma_f32_16x16x32_bf16 v[6:9], v[158:161], v[224:227], v[6:9]
	v_mfma_f32_16x16x32_bf16 v[58:61], v[162:165], v[178:181], v[58:61]
	v_mfma_f32_16x16x32_bf16 v[50:53], v[170:173], v[178:181], v[50:53]
	v_mfma_f32_16x16x32_bf16 v[42:45], v[162:165], v[186:189], v[42:45]
	v_mfma_f32_16x16x32_bf16 v[34:37], v[170:173], v[186:189], v[34:37]
	v_mfma_f32_16x16x32_bf16 v[26:29], v[162:165], v[202:205], v[26:29]
	v_mfma_f32_16x16x32_bf16 v[18:21], v[170:173], v[202:205], v[18:21]
	v_mfma_f32_16x16x32_bf16 v[10:13], v[162:165], v[220:223], v[10:13]
	v_mfma_f32_16x16x32_bf16 v[2:5], v[170:173], v[220:223], v[2:5]
	v_mfma_f32_16x16x32_bf16 v[58:61], v[166:169], v[182:185], v[58:61]
	v_mfma_f32_16x16x32_bf16 v[50:53], v[174:177], v[182:185], v[50:53]
	v_mfma_f32_16x16x32_bf16 v[42:45], v[166:169], v[190:193], v[42:45]
	v_mfma_f32_16x16x32_bf16 v[34:37], v[174:177], v[190:193], v[34:37]
	v_mfma_f32_16x16x32_bf16 v[26:29], v[166:169], v[206:209], v[26:29]
	v_mfma_f32_16x16x32_bf16 v[18:21], v[174:177], v[206:209], v[18:21]
	v_mfma_f32_16x16x32_bf16 v[10:13], v[166:169], v[224:227], v[10:13]
	v_mfma_f32_16x16x32_bf16 v[2:5], v[174:177], v[224:227], v[2:5]
	s_barrier
	s_add_i32 s51, 0, 0x18000
	s_add_i32 s52, 0, 0x1c000
	v_add_u32_e32 v158, s51, v143
	v_add_u32_e32 v174, s52, v143
	ds_read_b128 v[146:149], v158
	ds_read_b128 v[150:153], v158 offset:1024
	ds_read_b128 v[154:157], v158 offset:2048
	ds_read_b128 v[158:161], v158 offset:3072
	ds_read_b128 v[162:165], v174
	ds_read_b128 v[166:169], v174 offset:1024
	ds_read_b128 v[170:173], v174 offset:2048
	ds_read_b128 v[174:177], v174 offset:3072
	s_add_u32 s28, s28, 0x40000
	s_addc_u32 s29, s29, 0
	s_mov_b32 m0, s40
	v_lshl_add_u64 v[210:211], s[28:29], 0, v[134:135]
	ds_read_b128 v[178:181], v145 offset:32768
	ds_read_b128 v[182:185], v145 offset:33792
	ds_read_b128 v[186:189], v145 offset:34816
	ds_read_b128 v[190:193], v145 offset:35840
	ds_read_b128 v[202:205], v145 offset:36864
	ds_read_b128 v[206:209], v145 offset:37888
	ds_read_b128 v[220:223], v145 offset:38912
	ds_read_b128 v[224:227], v145 offset:39936
	global_load_lds_dwordx4 v[210:211], off
	v_lshl_add_u64 v[210:211], s[28:29], 0, v[132:133]
	s_mov_b32 m0, s41
	s_nop 0
	global_load_lds_dwordx4 v[210:211], off
	s_waitcnt vmcnt(8)
	s_waitcnt lgkmcnt(0)
	s_barrier
	s_waitcnt lgkmcnt(0)
	v_mfma_f32_16x16x32_bf16 v[126:129], v[146:149], v[178:181], v[126:129]
	v_mfma_f32_16x16x32_bf16 v[118:121], v[154:157], v[178:181], v[118:121]
	v_mfma_f32_16x16x32_bf16 v[110:113], v[146:149], v[186:189], v[110:113]
	v_mfma_f32_16x16x32_bf16 v[102:105], v[154:157], v[186:189], v[102:105]
	v_mfma_f32_16x16x32_bf16 v[94:97], v[146:149], v[202:205], v[94:97]
	v_mfma_f32_16x16x32_bf16 v[86:89], v[154:157], v[202:205], v[86:89]
	v_mfma_f32_16x16x32_bf16 v[78:81], v[146:149], v[220:223], v[78:81]
	v_mfma_f32_16x16x32_bf16 v[70:73], v[154:157], v[220:223], v[70:73]
	v_mfma_f32_16x16x32_bf16 v[126:129], v[150:153], v[182:185], v[126:129]
	v_mfma_f32_16x16x32_bf16 v[118:121], v[158:161], v[182:185], v[118:121]
	v_mfma_f32_16x16x32_bf16 v[110:113], v[150:153], v[190:193], v[110:113]
	v_mfma_f32_16x16x32_bf16 v[102:105], v[158:161], v[190:193], v[102:105]
	v_mfma_f32_16x16x32_bf16 v[94:97], v[150:153], v[206:209], v[94:97]
	v_mfma_f32_16x16x32_bf16 v[86:89], v[158:161], v[206:209], v[86:89]
	v_mfma_f32_16x16x32_bf16 v[78:81], v[150:153], v[224:227], v[78:81]
	v_mfma_f32_16x16x32_bf16 v[70:73], v[158:161], v[224:227], v[70:73]
	v_mfma_f32_16x16x32_bf16 v[122:125], v[162:165], v[178:181], v[122:125]
	v_mfma_f32_16x16x32_bf16 v[114:117], v[170:173], v[178:181], v[114:117]
	v_mfma_f32_16x16x32_bf16 v[106:109], v[162:165], v[186:189], v[106:109]
	v_mfma_f32_16x16x32_bf16 v[98:101], v[170:173], v[186:189], v[98:101]
	v_mfma_f32_16x16x32_bf16 v[90:93], v[162:165], v[202:205], v[90:93]
	v_mfma_f32_16x16x32_bf16 v[82:85], v[170:173], v[202:205], v[82:85]
	v_mfma_f32_16x16x32_bf16 v[74:77], v[162:165], v[220:223], v[74:77]
	v_mfma_f32_16x16x32_bf16 v[66:69], v[170:173], v[220:223], v[66:69]
	v_mfma_f32_16x16x32_bf16 v[122:125], v[166:169], v[182:185], v[122:125]
	v_mfma_f32_16x16x32_bf16 v[114:117], v[174:177], v[182:185], v[114:117]
	v_mfma_f32_16x16x32_bf16 v[106:109], v[166:169], v[190:193], v[106:109]
	v_mfma_f32_16x16x32_bf16 v[98:101], v[174:177], v[190:193], v[98:101]
	v_mfma_f32_16x16x32_bf16 v[90:93], v[166:169], v[206:209], v[90:93]
	v_mfma_f32_16x16x32_bf16 v[82:85], v[174:177], v[206:209], v[82:85]
	v_mfma_f32_16x16x32_bf16 v[74:77], v[166:169], v[224:227], v[74:77]
	v_mfma_f32_16x16x32_bf16 v[66:69], v[174:177], v[224:227], v[66:69]
	s_barrier
	s_add_i32 s28, s51, s36
	v_lshl_add_u64 v[140:141], v[140:141], 0, s[84:85]
	s_mov_b32 m0, s28
	ds_read_b128 v[178:181], v145 offset:49152
	ds_read_b128 v[182:185], v145 offset:50176
	ds_read_b128 v[186:189], v145 offset:51200
	ds_read_b128 v[190:193], v145 offset:52224
	ds_read_b128 v[202:205], v145 offset:53248
	ds_read_b128 v[206:209], v145 offset:54272
	ds_read_b128 v[220:223], v145 offset:55296
	ds_read_b128 v[224:227], v145 offset:56320
	global_load_lds_dwordx4 v[140:141], off
	s_add_i32 m0, s28, 0x2000
	s_add_u32 s20, s20, 0x40080
	v_lshl_add_u64 v[140:141], v[194:195], 0, s[84:85]
	s_addc_u32 s21, s21, 0
	s_add_i32 s28, s52, s36
	global_load_lds_dwordx4 v[140:141], off
	v_lshl_add_u64 v[140:141], s[20:21], 0, v[0:1]
	s_mov_b32 m0, s28
	s_nop 0
	global_load_lds_dwordx4 v[140:141], off
	v_lshl_add_u64 v[140:141], s[20:21], 0, v[130:131]
	s_add_i32 m0, s28, 0x2000
	s_nop 0
	global_load_lds_dwordx4 v[140:141], off
	v_lshl_add_u64 v[140:141], v[198:199], 0, s[84:85]
	s_mov_b32 m0, s76
	s_nop 0
	global_load_lds_dwordx4 v[140:141], off
	v_lshl_add_u64 v[140:141], v[200:201], 0, s[84:85]
	s_mov_b32 m0, s77
	s_nop 0
	global_load_lds_dwordx4 v[140:141], off
	s_waitcnt vmcnt(8)
	s_waitcnt lgkmcnt(0)
	s_barrier
	s_waitcnt lgkmcnt(0)
	v_mfma_f32_16x16x32_bf16 v[62:65], v[146:149], v[178:181], v[62:65]
	v_mfma_f32_16x16x32_bf16 v[54:57], v[154:157], v[178:181], v[54:57]
	v_mfma_f32_16x16x32_bf16 v[46:49], v[146:149], v[186:189], v[46:49]
	v_mfma_f32_16x16x32_bf16 v[38:41], v[154:157], v[186:189], v[38:41]
	v_mfma_f32_16x16x32_bf16 v[30:33], v[146:149], v[202:205], v[30:33]
	v_mfma_f32_16x16x32_bf16 v[22:25], v[154:157], v[202:205], v[22:25]
	v_mfma_f32_16x16x32_bf16 v[14:17], v[146:149], v[220:223], v[14:17]
	v_mfma_f32_16x16x32_bf16 v[6:9], v[154:157], v[220:223], v[6:9]
	v_mfma_f32_16x16x32_bf16 v[62:65], v[150:153], v[182:185], v[62:65]
	v_mfma_f32_16x16x32_bf16 v[54:57], v[158:161], v[182:185], v[54:57]
	v_mfma_f32_16x16x32_bf16 v[46:49], v[150:153], v[190:193], v[46:49]
	v_mfma_f32_16x16x32_bf16 v[38:41], v[158:161], v[190:193], v[38:41]
	v_mfma_f32_16x16x32_bf16 v[30:33], v[150:153], v[206:209], v[30:33]
	v_mfma_f32_16x16x32_bf16 v[22:25], v[158:161], v[206:209], v[22:25]
	v_mfma_f32_16x16x32_bf16 v[14:17], v[150:153], v[224:227], v[14:17]
	v_mfma_f32_16x16x32_bf16 v[6:9], v[158:161], v[224:227], v[6:9]
	v_mfma_f32_16x16x32_bf16 v[58:61], v[162:165], v[178:181], v[58:61]
	v_mfma_f32_16x16x32_bf16 v[50:53], v[170:173], v[178:181], v[50:53]
	v_mfma_f32_16x16x32_bf16 v[42:45], v[162:165], v[186:189], v[42:45]
	v_mfma_f32_16x16x32_bf16 v[34:37], v[170:173], v[186:189], v[34:37]
	v_mfma_f32_16x16x32_bf16 v[26:29], v[162:165], v[202:205], v[26:29]
	v_mfma_f32_16x16x32_bf16 v[18:21], v[170:173], v[202:205], v[18:21]
	v_mfma_f32_16x16x32_bf16 v[10:13], v[162:165], v[220:223], v[10:13]
	v_mfma_f32_16x16x32_bf16 v[2:5], v[170:173], v[220:223], v[2:5]
	v_mfma_f32_16x16x32_bf16 v[58:61], v[166:169], v[182:185], v[58:61]
	v_mfma_f32_16x16x32_bf16 v[50:53], v[174:177], v[182:185], v[50:53]
	v_mfma_f32_16x16x32_bf16 v[42:45], v[166:169], v[190:193], v[42:45]
	v_mfma_f32_16x16x32_bf16 v[34:37], v[174:177], v[190:193], v[34:37]
	v_mfma_f32_16x16x32_bf16 v[26:29], v[166:169], v[206:209], v[26:29]
	v_mfma_f32_16x16x32_bf16 v[18:21], v[174:177], v[206:209], v[18:21]
	v_mfma_f32_16x16x32_bf16 v[10:13], v[166:169], v[224:227], v[10:13]
	v_mfma_f32_16x16x32_bf16 v[2:5], v[174:177], v[224:227], v[2:5]
	s_barrier
	s_add_i32 s50, s50, 2
	s_add_u32 s4, s4, 0x100
	s_addc_u32 s5, s5, 0
	s_add_u32 s48, s48, 0x100
	s_addc_u32 s49, s49, 0
	s_cmp_gt_u32 s50, 13
	s_cbranch_scc0 .LBB0_692
